# speedup vs baseline: 1.0445x; 1.0140x over previous
; DI_ int kvmap(int rho) { return (rho & 0x13) | ((rho & 4) << 1) | ((rho & 8) >> 1); }
; #define AT_FETCH(S, tp_) do { const size_t kvb_ = (size_t)(tp_) * 128; k0##S = *(const u32x4*)(kg + kvb_ * D); k1##S = *(const u32x4*)(kg + (kvb_ + 64) * D); v0##S = *(const u32x4*)(vg + kvb_); v1##S = *(const u32x4*)(vg + (size_t)32 * VP + kvb_); \
;         cr##S = cp[kvb_ + tk] * (double)LOG2E; } while (0)
; DI_ void attn_unit(int bh, int qb, const bf16_t* Q, const bf16_t* Kg, const bf16_t* VT, const double* c64, const unsigned* kmax, bf16_t* O, unsigned char* lds, int tid, int lane, int wid) {
;     ...
;     float l_run = 0.f, thr = -INFINITY; f32x16 o0, o1;
; #pragma unroll
;     for (int i = 0; i < 16; ++i) { o0[i] = 0.f; o1[i] = 0.f; }
;     __syncthreads();
;     const double wo0 = woff[tw], wo1 = woff[tw + 4];
;     ...
;     AT_PUBLISH(A, lds);
;     AT_FETCH(A, NP - 2);
;     __syncthreads();
;     const int krow = kvmap(r32);
.LBB0_244:
	s_or_b64 exec, exec, s[10:11]
	v_add_u32_e32 v0, -2, v209
	v_lshlrev_b64 v[24:25], 8, v[0:1]
	v_lshl_add_u64 v[26:27], v[166:167], 0, v[24:25]
	v_lshl_add_u64 v[24:25], v[168:169], 0, v[24:25]
	s_waitcnt lgkmcnt(0)
	s_barrier
	v_lshlrev_b64 v[20:21], 18, v[0:1]
	global_load_dwordx4 v[122:125], v[26:27], off
	global_load_dwordx4 v[126:129], v[24:25], off
	v_lshlrev_b64 v[24:25], 10, v[0:1]
	v_lshl_add_u64 v[20:21], v[164:165], 0, v[20:21]
	v_lshl_add_u64 v[24:25], v[18:19], 0, v[24:25]
	v_add_co_u32_e32 v22, vcc, s49, v20
	v_lshl_add_u64 v[24:25], v[24:25], 0, v[154:155]
	s_nop 0
	v_addc_co_u32_e32 v23, vcc, 0, v21, vcc
	global_load_dwordx2 v[244:245], v[24:25], off
	global_load_dwordx4 v[114:117], v[20:21], off
	global_load_dwordx4 v[118:121], v[22:23], off
	ds_read_b64 v[170:171], v184
	ds_read_b64 v[172:173], v185
	s_mov_b32 s30, s28
	ds_write_b128 v205, v[2:5]
	s_waitcnt vmcnt(5)
	ds_write_b128 v205, v[6:9] offset:9216
	ds_write_b128 v206, v[10:13] offset:18432
	ds_write_b128 v206, v[14:17] offset:27136
	v_mov_b32_e32 v14, v1
	v_mov_b32_e32 v15, v1
	s_waitcnt lgkmcnt(5)
	v_fma_f64 v[16:17], s[30:31], v[34:35], v[170:171]
	s_waitcnt lgkmcnt(4)
	v_fma_f64 v[34:35], s[30:31], v[34:35], v[172:173]
	v_add_u32_e32 v161, 0, v186
	v_lshl_add_u64 v[174:175], v[18:19], 0, v[154:155]
	v_mov_b32_e32 v2, v1
	v_mov_b32_e32 v3, v1
	v_mov_b32_e32 v4, v1
	v_mov_b32_e32 v5, v1
	v_mov_b32_e32 v6, v1
	v_mov_b32_e32 v7, v1
	v_mov_b32_e32 v8, v1
	v_mov_b32_e32 v9, v1
	v_mov_b32_e32 v10, v1
	v_mov_b32_e32 v11, v1
	v_mov_b32_e32 v12, v1
	v_mov_b32_e32 v13, v1
	v_mov_b32_e32 v0, v1
	v_mov_b64_e32 v[32:33], v[14:15]
	v_cvt_f32_f64_e32 v16, v[16:17]
	v_cvt_f32_f64_e32 v17, v[34:35]
	v_add_u32_e32 v163, 0, v188
	v_mov_b64_e32 v[30:31], v[12:13]
	v_mov_b64_e32 v[28:29], v[10:11]
	v_mov_b64_e32 v[26:27], v[8:9]
	v_mov_b64_e32 v[24:25], v[6:7]
	v_mov_b64_e32 v[22:23], v[4:5]
	v_mov_b64_e32 v[20:21], v[2:3]
	v_mov_b64_e32 v[18:19], v[0:1]
	ds_write_b32 v161, v16 offset:35840
	ds_write_b32 v163, v17 offset:35840
	v_mov_b64_e32 v[16:17], v[14:15]
	v_or_b32_e32 v157, 31, v160
	s_mov_b32 s53, 0
	v_add_u32_e32 v176, -4, v209
	v_add_u32_e32 v155, v148, v208
	v_mov_b32_e32 v211, 0xff800000
	v_mov_b32_e32 v210, 0
	v_mov_b64_e32 v[178:179], 0
	s_mov_b32 s54, 2
	s_mov_b64 s[36:37], 0
	v_mov_b64_e32 v[14:15], v[12:13]
	v_mov_b64_e32 v[12:13], v[10:11]
	v_mov_b64_e32 v[10:11], v[8:9]
	v_mov_b64_e32 v[8:9], v[6:7]
	v_mov_b64_e32 v[6:7], v[4:5]
	v_mov_b64_e32 v[4:5], v[2:3]
	v_mov_b64_e32 v[2:3], v[0:1]
	s_waitcnt lgkmcnt(0)
	s_barrier
	s_branch .LBB0_246

.LBB0_250:
	v_add_u32_e32 v177, 3, v176
	v_cmp_lt_i32_e32 vcc, 1, v177
	s_and_saveexec_b64 s[10:11], vcc
	s_cbranch_execz .LBB0_252
	v_add_u32_e32 v0, 1, v176
	v_lshlrev_b64 v[34:35], 18, v[0:1]
	v_lshl_add_u64 v[34:35], v[164:165], 0, v[34:35]
	v_add_co_u32_e32 v36, vcc, 0x20000, v34
	v_lshlrev_b64 v[38:39], 10, v[0:1]
	s_nop 0
	v_addc_co_u32_e32 v37, vcc, 0, v35, vcc
	global_load_dwordx4 v[130:133], v[34:35], off
	global_load_dwordx4 v[134:137], v[36:37], off
	v_lshlrev_b64 v[34:35], 8, v[0:1]
	v_lshl_add_u64 v[38:39], v[174:175], 0, v[38:39]
	v_lshl_add_u64 v[36:37], v[166:167], 0, v[34:35]
	v_lshl_add_u64 v[34:35], v[168:169], 0, v[34:35]
	global_load_dwordx2 v[246:247], v[38:39], off
	s_nop 0
	global_load_dwordx4 v[138:141], v[36:37], off
	global_load_dwordx4 v[142:145], v[34:35], off
.LBB0_252:
	s_or_b64 exec, exec, s[10:11]
	v_add_u32_e32 v0, s53, v208
	v_add_u32_e32 v34, 0x80, v0
	v_cmp_le_i32_e32 vcc, v34, v157
	s_mov_b64 s[40:41], 0
	s_and_saveexec_b64 s[10:11], vcc
	s_cbranch_execz .LBB0_262
	v_add_u32_e32 v194, v191, v203
	v_add_u32_e32 v46, s33, v189
	ds_read_b128 v[220:223], v194
	ds_read_b128 v[82:85], v46 offset:35840
	ds_read_b128 v[86:89], v46 offset:35856
	ds_read_b128 v[90:93], v46 offset:35904
	ds_read_b128 v[94:97], v46 offset:35920
	ds_read_b128 v[224:227], v194 offset:4608
	ds_read_b128 v[66:69], v46 offset:35968
	ds_read_b128 v[70:73], v46 offset:35984
	ds_read_b128 v[74:77], v46 offset:36032
	ds_read_b128 v[78:81], v46 offset:36048
	ds_read_b128 v[228:231], v194 offset:9216
	ds_read_b128 v[50:53], v46 offset:36096
	ds_read_b128 v[54:57], v46 offset:36112
	ds_read_b128 v[58:61], v46 offset:36160
	ds_read_b128 v[62:65], v46 offset:36176
	ds_read_b128 v[232:235], v194 offset:13824
	ds_read_b128 v[34:37], v46 offset:36224
	ds_read_b128 v[38:41], v46 offset:36240
	ds_read_b128 v[42:45], v46 offset:36288
	ds_read_b128 v[46:49], v46 offset:36304
	ds_read_b128 v[236:239], v194 offset:32
	ds_read_b128 v[240:243], v194 offset:4640
	v_add_u32_e32 v0, 0xff, v0
	v_cmp_gt_i32_e32 vcc, v0, v160
	s_waitcnt lgkmcnt(15)
	v_mfma_f32_32x32x16_bf16 v[82:97], v[220:223], v[98:101], v[82:97]
	ds_read_b128 v[220:223], v194 offset:9248
	s_waitcnt lgkmcnt(13)
	v_mfma_f32_32x32x16_bf16 v[66:81], v[224:227], v[98:101], v[66:81]
	ds_read_b128 v[224:227], v194 offset:13856
	s_waitcnt lgkmcnt(9)
	v_mfma_f32_32x32x16_bf16 v[50:65], v[228:231], v[98:101], v[50:65]
	ds_read_b128 v[228:231], v194 offset:64
	s_waitcnt lgkmcnt(5)
	v_mfma_f32_32x32x16_bf16 v[34:49], v[232:235], v[98:101], v[34:49]
	ds_read_b128 v[232:235], v194 offset:4672
	s_waitcnt lgkmcnt(5)
	v_mfma_f32_32x32x16_bf16 v[82:97], v[236:239], v[102:105], v[82:97]
	ds_read_b128 v[236:239], v194 offset:9280
	s_waitcnt lgkmcnt(5)
	v_mfma_f32_32x32x16_bf16 v[66:81], v[240:243], v[102:105], v[66:81]
	ds_read_b128 v[240:243], v194 offset:13888
	s_waitcnt lgkmcnt(5)
	v_mfma_f32_32x32x16_bf16 v[50:65], v[220:223], v[102:105], v[50:65]
	ds_read_b128 v[220:223], v194 offset:96
	s_waitcnt lgkmcnt(5)
	v_mfma_f32_32x32x16_bf16 v[34:49], v[224:227], v[102:105], v[34:49]
	ds_read_b128 v[224:227], v194 offset:4704
	s_waitcnt lgkmcnt(5)
	v_mfma_f32_32x32x16_bf16 v[82:97], v[228:231], v[106:109], v[82:97]
	ds_read_b128 v[228:231], v194 offset:9312
	s_waitcnt lgkmcnt(5)
	v_mfma_f32_32x32x16_bf16 v[66:81], v[232:235], v[106:109], v[66:81]
	ds_read_b128 v[232:235], v194 offset:13920
	s_waitcnt lgkmcnt(5)
	v_mfma_f32_32x32x16_bf16 v[50:65], v[236:239], v[106:109], v[50:65]
	s_waitcnt lgkmcnt(4)
	v_mfma_f32_32x32x16_bf16 v[34:49], v[240:243], v[106:109], v[34:49]
	s_waitcnt lgkmcnt(3)
	v_mfma_f32_32x32x16_bf16 v[82:97], v[220:223], v[110:113], v[82:97]
	s_waitcnt lgkmcnt(2)
	v_mfma_f32_32x32x16_bf16 v[66:81], v[224:227], v[110:113], v[66:81]
	s_waitcnt lgkmcnt(1)
	v_mfma_f32_32x32x16_bf16 v[50:65], v[228:231], v[110:113], v[50:65]
	s_waitcnt lgkmcnt(0)
	v_mfma_f32_32x32x16_bf16 v[34:49], v[232:235], v[110:113], v[34:49]
	s_and_saveexec_b64 s[40:41], vcc
	s_cbranch_execz .LBB0_255
	v_add_u32_e32 v0, s53, v155
	v_add_u32_e32 v194, 0x80, v0
	v_cmp_lt_i32_e32 vcc, v194, v162
	s_nop 1
	v_cndmask_b32_e32 v83, v207, v83, vcc
	v_cmp_le_i32_e32 vcc, v194, v162
	v_add_u32_e32 v194, 0x82, v0
	s_nop 0
	v_cndmask_b32_e32 v82, v207, v82, vcc
	v_cmp_le_i32_e32 vcc, v194, v162
	v_add_u32_e32 v194, 0x83, v0
	s_nop 0
	v_cndmask_b32_e32 v84, v207, v84, vcc
	v_cmp_le_i32_e32 vcc, v194, v162
	v_add_u32_e32 v194, 0x84, v0
	s_nop 0
	v_cndmask_b32_e32 v85, v207, v85, vcc
	v_cmp_le_i32_e32 vcc, v194, v162
	v_add_u32_e32 v194, 0x85, v0
	s_nop 0
	v_cndmask_b32_e32 v86, v207, v86, vcc
	v_cmp_le_i32_e32 vcc, v194, v162
	v_add_u32_e32 v194, 0x86, v0
	s_nop 0
	v_cndmask_b32_e32 v87, v207, v87, vcc
	v_cmp_le_i32_e32 vcc, v194, v162
	v_add_u32_e32 v194, 0x87, v0
	s_nop 0
	v_cndmask_b32_e32 v88, v207, v88, vcc
	v_cmp_le_i32_e32 vcc, v194, v162
	v_add_u32_e32 v194, 0x90, v0
	s_nop 0
	v_cndmask_b32_e32 v89, v207, v89, vcc
	v_cmp_le_i32_e32 vcc, v194, v162
	v_add_u32_e32 v194, 0x91, v0
	s_nop 0
	v_cndmask_b32_e32 v90, v207, v90, vcc
	v_cmp_le_i32_e32 vcc, v194, v162
	v_add_u32_e32 v194, 0x92, v0
	s_nop 0
	v_cndmask_b32_e32 v91, v207, v91, vcc
	v_cmp_le_i32_e32 vcc, v194, v162
	v_add_u32_e32 v194, 0x93, v0
	s_nop 0
	v_cndmask_b32_e32 v92, v207, v92, vcc
	v_cmp_le_i32_e32 vcc, v194, v162
	v_add_u32_e32 v194, 0x94, v0
	s_nop 0
	v_cndmask_b32_e32 v93, v207, v93, vcc
	v_cmp_le_i32_e32 vcc, v194, v162
	v_add_u32_e32 v194, 0x95, v0
	s_nop 0
	v_cndmask_b32_e32 v94, v207, v94, vcc
	v_cmp_le_i32_e32 vcc, v194, v162
	v_add_u32_e32 v194, 0x96, v0
	s_nop 0
	v_cndmask_b32_e32 v95, v207, v95, vcc
	v_cmp_le_i32_e32 vcc, v194, v162
	v_add_u32_e32 v194, 0x97, v0
	s_nop 0
	v_cndmask_b32_e32 v96, v207, v96, vcc
	v_cmp_le_i32_e32 vcc, v194, v162
	v_add_u32_e32 v194, 0xa0, v0
	s_nop 0
	v_cndmask_b32_e32 v97, v207, v97, vcc
	v_cmp_le_i32_e32 vcc, v194, v162
	v_add_u32_e32 v194, 0xa1, v0
	s_nop 0
	v_cndmask_b32_e32 v66, v207, v66, vcc
	v_cmp_le_i32_e32 vcc, v194, v162
	v_add_u32_e32 v194, 0xa2, v0
	s_nop 0
	v_cndmask_b32_e32 v67, v207, v67, vcc
	v_cmp_le_i32_e32 vcc, v194, v162
	v_add_u32_e32 v194, 0xa3, v0
	s_nop 0
	v_cndmask_b32_e32 v68, v207, v68, vcc
	v_cmp_le_i32_e32 vcc, v194, v162
	v_add_u32_e32 v194, 0xa4, v0
	s_nop 0
	v_cndmask_b32_e32 v69, v207, v69, vcc
	v_cmp_le_i32_e32 vcc, v194, v162
	v_add_u32_e32 v194, 0xa5, v0
	s_nop 0
	v_cndmask_b32_e32 v70, v207, v70, vcc
	v_cmp_le_i32_e32 vcc, v194, v162
	v_add_u32_e32 v194, 0xa6, v0
	s_nop 0
	v_cndmask_b32_e32 v71, v207, v71, vcc
	v_cmp_le_i32_e32 vcc, v194, v162
	v_add_u32_e32 v194, 0xa7, v0
	s_nop 0
	v_cndmask_b32_e32 v72, v207, v72, vcc
	v_cmp_le_i32_e32 vcc, v194, v162
	v_add_u32_e32 v194, 0xb0, v0
	s_nop 0
	v_cndmask_b32_e32 v73, v207, v73, vcc
	v_cmp_le_i32_e32 vcc, v194, v162
	v_add_u32_e32 v194, 0xb1, v0
	s_nop 0
	v_cndmask_b32_e32 v74, v207, v74, vcc
	v_cmp_le_i32_e32 vcc, v194, v162
	v_add_u32_e32 v194, 0xb2, v0
	s_nop 0
	v_cndmask_b32_e32 v75, v207, v75, vcc
	v_cmp_le_i32_e32 vcc, v194, v162
	v_add_u32_e32 v194, 0xb3, v0
	s_nop 0
	v_cndmask_b32_e32 v76, v207, v76, vcc
	v_cmp_le_i32_e32 vcc, v194, v162
	v_add_u32_e32 v194, 0xb4, v0
	s_nop 0
	v_cndmask_b32_e32 v77, v207, v77, vcc
	v_cmp_le_i32_e32 vcc, v194, v162
	v_add_u32_e32 v194, 0xb5, v0
	s_nop 0
	v_cndmask_b32_e32 v78, v207, v78, vcc
	v_cmp_le_i32_e32 vcc, v194, v162
	v_add_u32_e32 v194, 0xb6, v0
	s_nop 0
	v_cndmask_b32_e32 v79, v207, v79, vcc
	v_cmp_le_i32_e32 vcc, v194, v162
	v_add_u32_e32 v194, 0xb7, v0
	s_nop 0
	v_cndmask_b32_e32 v80, v207, v80, vcc
	v_cmp_le_i32_e32 vcc, v194, v162
	v_add_u32_e32 v194, 0xc0, v0
	s_nop 0
	v_cndmask_b32_e32 v81, v207, v81, vcc
	v_cmp_le_i32_e32 vcc, v194, v162
	v_add_u32_e32 v194, 0xc1, v0
	s_nop 0
	v_cndmask_b32_e32 v50, v207, v50, vcc
	v_cmp_le_i32_e32 vcc, v194, v162
	v_add_u32_e32 v194, 0xc2, v0
	s_nop 0
	v_cndmask_b32_e32 v51, v207, v51, vcc
	v_cmp_le_i32_e32 vcc, v194, v162
	v_add_u32_e32 v194, 0xc3, v0
	s_nop 0
	v_cndmask_b32_e32 v52, v207, v52, vcc
	v_cmp_le_i32_e32 vcc, v194, v162
	v_add_u32_e32 v194, 0xc4, v0
	s_nop 0
	v_cndmask_b32_e32 v53, v207, v53, vcc
	v_cmp_le_i32_e32 vcc, v194, v162
	v_add_u32_e32 v194, 0xc5, v0
	s_nop 0
	v_cndmask_b32_e32 v54, v207, v54, vcc
	v_cmp_le_i32_e32 vcc, v194, v162
	v_add_u32_e32 v194, 0xc6, v0
	s_nop 0
	v_cndmask_b32_e32 v55, v207, v55, vcc
	v_cmp_le_i32_e32 vcc, v194, v162
	v_add_u32_e32 v194, 0xc7, v0
	s_nop 0
	v_cndmask_b32_e32 v56, v207, v56, vcc
	v_cmp_le_i32_e32 vcc, v194, v162
	v_add_u32_e32 v194, 0xd0, v0
	s_nop 0
	v_cndmask_b32_e32 v57, v207, v57, vcc
	v_cmp_le_i32_e32 vcc, v194, v162
	v_add_u32_e32 v194, 0xd1, v0
	s_nop 0
	v_cndmask_b32_e32 v58, v207, v58, vcc
	v_cmp_le_i32_e32 vcc, v194, v162
	v_add_u32_e32 v194, 0xd2, v0
	s_nop 0
	v_cndmask_b32_e32 v59, v207, v59, vcc
	v_cmp_le_i32_e32 vcc, v194, v162
	v_add_u32_e32 v194, 0xd3, v0
	s_nop 0
	v_cndmask_b32_e32 v60, v207, v60, vcc
	v_cmp_le_i32_e32 vcc, v194, v162
	v_add_u32_e32 v194, 0xd4, v0
	s_nop 0
	v_cndmask_b32_e32 v61, v207, v61, vcc
	v_cmp_le_i32_e32 vcc, v194, v162
	v_add_u32_e32 v194, 0xd5, v0
	s_nop 0
	v_cndmask_b32_e32 v62, v207, v62, vcc
	v_cmp_le_i32_e32 vcc, v194, v162
	v_add_u32_e32 v194, 0xd6, v0
	s_nop 0
	v_cndmask_b32_e32 v63, v207, v63, vcc
	v_cmp_le_i32_e32 vcc, v194, v162
	v_add_u32_e32 v194, 0xd7, v0
	s_nop 0
	v_cndmask_b32_e32 v64, v207, v64, vcc
	v_cmp_le_i32_e32 vcc, v194, v162
	v_add_u32_e32 v194, 0xe0, v0
	s_nop 0
	v_cndmask_b32_e32 v65, v207, v65, vcc
	v_cmp_le_i32_e32 vcc, v194, v162
	v_add_u32_e32 v194, 0xe1, v0
	s_nop 0
	v_cndmask_b32_e32 v34, v207, v34, vcc
	v_cmp_le_i32_e32 vcc, v194, v162
	v_add_u32_e32 v194, 0xe2, v0
	s_nop 0
	v_cndmask_b32_e32 v35, v207, v35, vcc
	v_cmp_le_i32_e32 vcc, v194, v162
	v_add_u32_e32 v194, 0xe3, v0
	s_nop 0
	v_cndmask_b32_e32 v36, v207, v36, vcc
	v_cmp_le_i32_e32 vcc, v194, v162
	v_add_u32_e32 v194, 0xe4, v0
	s_nop 0
	v_cndmask_b32_e32 v37, v207, v37, vcc
	v_cmp_le_i32_e32 vcc, v194, v162
	v_add_u32_e32 v194, 0xe5, v0
	s_nop 0
	v_cndmask_b32_e32 v38, v207, v38, vcc
	v_cmp_le_i32_e32 vcc, v194, v162
	v_add_u32_e32 v194, 0xe6, v0
	s_nop 0
	v_cndmask_b32_e32 v39, v207, v39, vcc
	v_cmp_le_i32_e32 vcc, v194, v162
	v_add_u32_e32 v194, 0xe7, v0
	s_nop 0
	v_cndmask_b32_e32 v40, v207, v40, vcc
	v_cmp_le_i32_e32 vcc, v194, v162
	v_add_u32_e32 v194, 0xf0, v0
	s_nop 0
	v_cndmask_b32_e32 v41, v207, v41, vcc
	v_cmp_le_i32_e32 vcc, v194, v162
	v_add_u32_e32 v194, 0xf1, v0
	s_nop 0
	v_cndmask_b32_e32 v42, v207, v42, vcc
	v_cmp_le_i32_e32 vcc, v194, v162
	v_add_u32_e32 v194, 0xf2, v0
	s_nop 0
	v_cndmask_b32_e32 v43, v207, v43, vcc
	v_cmp_le_i32_e32 vcc, v194, v162
	v_add_u32_e32 v194, 0xf3, v0
	s_nop 0
	v_cndmask_b32_e32 v44, v207, v44, vcc
	v_cmp_le_i32_e32 vcc, v194, v162
	v_add_u32_e32 v194, 0xf4, v0
	s_nop 0
	v_cndmask_b32_e32 v45, v207, v45, vcc
	v_cmp_le_i32_e32 vcc, v194, v162
	v_add_u32_e32 v194, 0xf5, v0
	s_nop 0
	v_cndmask_b32_e32 v46, v207, v46, vcc
	v_cmp_le_i32_e32 vcc, v194, v162
	v_add_u32_e32 v194, 0xf6, v0
	v_add_u32_e32 v0, 0xf7, v0
	v_cndmask_b32_e32 v47, v207, v47, vcc
	v_cmp_le_i32_e32 vcc, v194, v162
	s_nop 1
	v_cndmask_b32_e32 v48, v207, v48, vcc
	v_cmp_le_i32_e32 vcc, v0, v162
	s_nop 1
	v_cndmask_b32_e32 v49, v207, v49, vcc

.LBB0_262:
	s_or_b64 exec, exec, s[10:11]
	v_cndmask_b32_e64 v0, 0, 1, s[40:41]
	s_mov_b64 s[42:43], exec
	v_cmp_ne_u32_e32 vcc, 0, v0
	s_and_saveexec_b64 s[10:11], s[6:7]
	s_cmp_eq_u64 vcc, s[42:43]
	s_cselect_b64 s[40:41], -1, 0
	v_cndmask_b32_e64 v0, 0, 1, s[40:41]
	v_mov_b32_e32 v34, s46
	ds_write_b32 v34, v0
	s_or_b64 exec, exec, s[10:11]
	v_cmp_lt_i32_e32 vcc, 0, v177
	s_and_saveexec_b64 s[10:11], vcc
	s_cbranch_execz .LBB0_266
	s_waitcnt vmcnt(2)
	v_mul_f64 v[180:181], v[244:245], s[28:29]
	v_add_f64 v[34:35], v[170:171], -v[180:181]
	s_add_i32 s30, 0, 0x12800
	v_cvt_f32_f64_e32 v0, v[34:35]
	v_add_u32_e32 v34, s30, v186
	s_waitcnt vmcnt(1)
	ds_write_b128 v205, v[114:117] offset:39936
	s_waitcnt vmcnt(0)
	ds_write_b128 v205, v[118:121] offset:49152
	ds_write_b128 v206, v[122:125] offset:58368
	ds_write_b128 v204, v[126:129] offset:8704
	ds_write_b32 v34, v0
	v_add_f64 v[34:35], v[172:173], -v[180:181]
	v_cvt_f32_f64_e32 v0, v[34:35]
	v_add_u32_e32 v34, s30, v188
	ds_write_b32 v34, v0

.LBB0_267:
	s_add_i32 s10, 0, 0x13800
	v_mov_b32_e32 v0, s10
	ds_read_b128 v[34:37], v0
	v_mov_b32_e32 v0, s52
	ds_read_b128 v[38:41], v0
	s_waitcnt lgkmcnt(1)
	v_and_b32_e32 v0, v34, v35
	v_and_b32_e32 v0, v0, v36
	v_and_b32_e32 v0, v0, v37
	s_waitcnt lgkmcnt(0)
	v_and_b32_e32 v0, v0, v38
	v_and_b32_e32 v0, v0, v39
	v_and_b32_e32 v0, v0, v40
	v_and_b32_e32 v0, v0, v41
	v_cmp_ne_u32_e32 vcc, 0, v0
	v_cmp_eq_u32_e64 s[10:11], 0, v0
	s_cbranch_vccnz .LBB0_285
	v_add_u32_e32 v0, 2, v176
	v_cmp_lt_i32_e32 vcc, 1, v0
	s_and_saveexec_b64 s[40:41], vcc
	s_cbranch_execz .LBB0_270
	v_mov_b32_e32 v177, v1
	v_lshlrev_b64 v[34:35], 18, v[176:177]
	v_lshl_add_u64 v[34:35], v[164:165], 0, v[34:35]
	v_add_co_u32_e32 v36, vcc, 0x20000, v34
	v_lshlrev_b64 v[38:39], 10, v[176:177]
	s_nop 0
	v_addc_co_u32_e32 v37, vcc, 0, v35, vcc
	global_load_dwordx4 v[114:117], v[34:35], off
	global_load_dwordx4 v[118:121], v[36:37], off
	v_lshlrev_b64 v[34:35], 8, v[176:177]
	v_lshl_add_u64 v[38:39], v[174:175], 0, v[38:39]
	v_lshl_add_u64 v[36:37], v[166:167], 0, v[34:35]
	v_lshl_add_u64 v[34:35], v[168:169], 0, v[34:35]
	global_load_dwordx2 v[244:245], v[38:39], off
	s_nop 0
	global_load_dwordx4 v[122:125], v[36:37], off
	global_load_dwordx4 v[126:129], v[34:35], off
.LBB0_270:
	s_or_b64 exec, exec, s[40:41]
	v_add_u32_e32 v177, s53, v208
	v_cmp_le_i32_e32 vcc, v177, v157
	s_mov_b64 s[42:43], 0
	s_and_saveexec_b64 s[40:41], vcc
	s_cbranch_execz .LBB0_280
	v_add_u32_e32 v194, v191, v203
	v_add_u32_e32 v46, s47, v189
	ds_read_b128 v[220:223], v194 offset:39936
	ds_read_b128 v[82:85], v46
	ds_read_b128 v[86:89], v46 offset:16
	ds_read_b128 v[90:93], v46 offset:64
	ds_read_b128 v[94:97], v46 offset:80
	ds_read_b128 v[224:227], v194 offset:44544
	ds_read_b128 v[66:69], v46 offset:128
	ds_read_b128 v[70:73], v46 offset:144
	ds_read_b128 v[74:77], v46 offset:192
	ds_read_b128 v[78:81], v46 offset:208
	ds_read_b128 v[228:231], v194 offset:49152
	ds_read_b128 v[50:53], v46 offset:256
	ds_read_b128 v[54:57], v46 offset:272
	ds_read_b128 v[58:61], v46 offset:320
	ds_read_b128 v[62:65], v46 offset:336
	ds_read_b128 v[232:235], v194 offset:53760
	ds_read_b128 v[34:37], v46 offset:384
	ds_read_b128 v[38:41], v46 offset:400
	ds_read_b128 v[42:45], v46 offset:448
	ds_read_b128 v[46:49], v46 offset:464
	ds_read_b128 v[236:239], v194 offset:39968
	ds_read_b128 v[240:243], v194 offset:44576
	v_add_u32_e32 v177, 0x7f, v177
	v_cmp_gt_i32_e32 vcc, v177, v160
	s_waitcnt lgkmcnt(15)
	v_mfma_f32_32x32x16_bf16 v[82:97], v[220:223], v[98:101], v[82:97]
	ds_read_b128 v[220:223], v194 offset:49184
	s_waitcnt lgkmcnt(13)
	v_mfma_f32_32x32x16_bf16 v[66:81], v[224:227], v[98:101], v[66:81]
	ds_read_b128 v[224:227], v194 offset:53792
	s_waitcnt lgkmcnt(9)
	v_mfma_f32_32x32x16_bf16 v[50:65], v[228:231], v[98:101], v[50:65]
	ds_read_b128 v[228:231], v194 offset:40000
	s_waitcnt lgkmcnt(5)
	v_mfma_f32_32x32x16_bf16 v[34:49], v[232:235], v[98:101], v[34:49]
	ds_read_b128 v[232:235], v194 offset:44608
	s_waitcnt lgkmcnt(5)
	v_mfma_f32_32x32x16_bf16 v[82:97], v[236:239], v[102:105], v[82:97]
	ds_read_b128 v[236:239], v194 offset:49216
	s_waitcnt lgkmcnt(5)
	v_mfma_f32_32x32x16_bf16 v[66:81], v[240:243], v[102:105], v[66:81]
	ds_read_b128 v[240:243], v194 offset:53824
	s_waitcnt lgkmcnt(5)
	v_mfma_f32_32x32x16_bf16 v[50:65], v[220:223], v[102:105], v[50:65]
	ds_read_b128 v[220:223], v194 offset:40032
	s_waitcnt lgkmcnt(5)
	v_mfma_f32_32x32x16_bf16 v[34:49], v[224:227], v[102:105], v[34:49]
	ds_read_b128 v[224:227], v194 offset:44640
	s_waitcnt lgkmcnt(5)
	v_mfma_f32_32x32x16_bf16 v[82:97], v[228:231], v[106:109], v[82:97]
	ds_read_b128 v[228:231], v194 offset:49248
	s_waitcnt lgkmcnt(5)
	v_mfma_f32_32x32x16_bf16 v[66:81], v[232:235], v[106:109], v[66:81]
	ds_read_b128 v[232:235], v194 offset:53856
	s_waitcnt lgkmcnt(5)
	v_mfma_f32_32x32x16_bf16 v[50:65], v[236:239], v[106:109], v[50:65]
	s_waitcnt lgkmcnt(4)
	v_mfma_f32_32x32x16_bf16 v[34:49], v[240:243], v[106:109], v[34:49]
	s_waitcnt lgkmcnt(3)
	v_mfma_f32_32x32x16_bf16 v[82:97], v[220:223], v[110:113], v[82:97]
	s_waitcnt lgkmcnt(2)
	v_mfma_f32_32x32x16_bf16 v[66:81], v[224:227], v[110:113], v[66:81]
	s_waitcnt lgkmcnt(1)
	v_mfma_f32_32x32x16_bf16 v[50:65], v[228:231], v[110:113], v[50:65]
	s_waitcnt lgkmcnt(0)
	v_mfma_f32_32x32x16_bf16 v[34:49], v[232:235], v[110:113], v[34:49]
	s_and_saveexec_b64 s[42:43], vcc
	s_cbranch_execz .LBB0_273
	v_add_u32_e32 v177, s53, v155
	v_cmp_lt_i32_e32 vcc, v177, v162
	v_add_u32_e32 v194, 2, v177
	s_nop 0
	v_cndmask_b32_e32 v83, v207, v83, vcc
	v_cmp_le_i32_e32 vcc, v177, v162
	s_nop 1
	v_cndmask_b32_e32 v82, v207, v82, vcc
	v_cmp_le_i32_e32 vcc, v194, v162
	v_add_u32_e32 v194, 3, v177
	s_nop 0
	v_cndmask_b32_e32 v84, v207, v84, vcc
	v_cmp_le_i32_e32 vcc, v194, v162
	v_add_u32_e32 v194, 4, v177
	s_nop 0
	v_cndmask_b32_e32 v85, v207, v85, vcc
	v_cmp_le_i32_e32 vcc, v194, v162
	v_add_u32_e32 v194, 5, v177
	s_nop 0
	v_cndmask_b32_e32 v86, v207, v86, vcc
	v_cmp_le_i32_e32 vcc, v194, v162
	v_add_u32_e32 v194, 6, v177
	s_nop 0
	v_cndmask_b32_e32 v87, v207, v87, vcc
	v_cmp_le_i32_e32 vcc, v194, v162
	v_add_u32_e32 v194, 7, v177
	s_nop 0
	v_cndmask_b32_e32 v88, v207, v88, vcc
	v_cmp_le_i32_e32 vcc, v194, v162
	v_add_u32_e32 v194, 16, v177
	s_nop 0
	v_cndmask_b32_e32 v89, v207, v89, vcc
	v_cmp_le_i32_e32 vcc, v194, v162
	v_add_u32_e32 v194, 17, v177
	s_nop 0
	v_cndmask_b32_e32 v90, v207, v90, vcc
	v_cmp_le_i32_e32 vcc, v194, v162
	v_add_u32_e32 v194, 18, v177
	s_nop 0
	v_cndmask_b32_e32 v91, v207, v91, vcc
	v_cmp_le_i32_e32 vcc, v194, v162
	v_add_u32_e32 v194, 19, v177
	s_nop 0
	v_cndmask_b32_e32 v92, v207, v92, vcc
	v_cmp_le_i32_e32 vcc, v194, v162
	v_add_u32_e32 v194, 20, v177
	s_nop 0
	v_cndmask_b32_e32 v93, v207, v93, vcc
	v_cmp_le_i32_e32 vcc, v194, v162
	v_add_u32_e32 v194, 21, v177
	s_nop 0
	v_cndmask_b32_e32 v94, v207, v94, vcc
	v_cmp_le_i32_e32 vcc, v194, v162
	v_add_u32_e32 v194, 22, v177
	s_nop 0
	v_cndmask_b32_e32 v95, v207, v95, vcc
	v_cmp_le_i32_e32 vcc, v194, v162
	v_add_u32_e32 v194, 23, v177
	s_nop 0
	v_cndmask_b32_e32 v96, v207, v96, vcc
	v_cmp_le_i32_e32 vcc, v194, v162
	v_add_u32_e32 v194, 32, v177
	s_nop 0
	v_cndmask_b32_e32 v97, v207, v97, vcc
	v_cmp_le_i32_e32 vcc, v194, v162
	v_add_u32_e32 v194, 33, v177
	s_nop 0
	v_cndmask_b32_e32 v66, v207, v66, vcc
	v_cmp_le_i32_e32 vcc, v194, v162
	v_add_u32_e32 v194, 34, v177
	s_nop 0
	v_cndmask_b32_e32 v67, v207, v67, vcc
	v_cmp_le_i32_e32 vcc, v194, v162
	v_add_u32_e32 v194, 35, v177
	s_nop 0
	v_cndmask_b32_e32 v68, v207, v68, vcc
	v_cmp_le_i32_e32 vcc, v194, v162
	v_add_u32_e32 v194, 36, v177
	s_nop 0
	v_cndmask_b32_e32 v69, v207, v69, vcc
	v_cmp_le_i32_e32 vcc, v194, v162
	v_add_u32_e32 v194, 37, v177
	s_nop 0
	v_cndmask_b32_e32 v70, v207, v70, vcc
	v_cmp_le_i32_e32 vcc, v194, v162
	v_add_u32_e32 v194, 38, v177
	s_nop 0
	v_cndmask_b32_e32 v71, v207, v71, vcc
	v_cmp_le_i32_e32 vcc, v194, v162
	v_add_u32_e32 v194, 39, v177
	s_nop 0
	v_cndmask_b32_e32 v72, v207, v72, vcc
	v_cmp_le_i32_e32 vcc, v194, v162
	v_add_u32_e32 v194, 48, v177
	s_nop 0
	v_cndmask_b32_e32 v73, v207, v73, vcc
	v_cmp_le_i32_e32 vcc, v194, v162
	v_add_u32_e32 v194, 49, v177
	s_nop 0
	v_cndmask_b32_e32 v74, v207, v74, vcc
	v_cmp_le_i32_e32 vcc, v194, v162
	v_add_u32_e32 v194, 50, v177
	s_nop 0
	v_cndmask_b32_e32 v75, v207, v75, vcc
	v_cmp_le_i32_e32 vcc, v194, v162
	v_add_u32_e32 v194, 51, v177
	s_nop 0
	v_cndmask_b32_e32 v76, v207, v76, vcc
	v_cmp_le_i32_e32 vcc, v194, v162
	v_add_u32_e32 v194, 52, v177
	s_nop 0
	v_cndmask_b32_e32 v77, v207, v77, vcc
	v_cmp_le_i32_e32 vcc, v194, v162
	v_add_u32_e32 v194, 53, v177
	s_nop 0
	v_cndmask_b32_e32 v78, v207, v78, vcc
	v_cmp_le_i32_e32 vcc, v194, v162
	v_add_u32_e32 v194, 54, v177
	s_nop 0
	v_cndmask_b32_e32 v79, v207, v79, vcc
	v_cmp_le_i32_e32 vcc, v194, v162
	v_add_u32_e32 v194, 55, v177
	s_nop 0
	v_cndmask_b32_e32 v80, v207, v80, vcc
	v_cmp_le_i32_e32 vcc, v194, v162
	v_add_u32_e32 v194, 64, v177
	s_nop 0
	v_cndmask_b32_e32 v81, v207, v81, vcc
	v_cmp_le_i32_e32 vcc, v194, v162
	v_add_u32_e32 v194, 0x41, v177
	s_nop 0
	v_cndmask_b32_e32 v50, v207, v50, vcc
	v_cmp_le_i32_e32 vcc, v194, v162
	v_add_u32_e32 v194, 0x42, v177
	s_nop 0
	v_cndmask_b32_e32 v51, v207, v51, vcc
	v_cmp_le_i32_e32 vcc, v194, v162
	v_add_u32_e32 v194, 0x43, v177
	s_nop 0
	v_cndmask_b32_e32 v52, v207, v52, vcc
	v_cmp_le_i32_e32 vcc, v194, v162
	v_add_u32_e32 v194, 0x44, v177
	s_nop 0
	v_cndmask_b32_e32 v53, v207, v53, vcc
	v_cmp_le_i32_e32 vcc, v194, v162
	v_add_u32_e32 v194, 0x45, v177
	s_nop 0
	v_cndmask_b32_e32 v54, v207, v54, vcc
	v_cmp_le_i32_e32 vcc, v194, v162
	v_add_u32_e32 v194, 0x46, v177
	s_nop 0
	v_cndmask_b32_e32 v55, v207, v55, vcc
	v_cmp_le_i32_e32 vcc, v194, v162
	v_add_u32_e32 v194, 0x47, v177
	s_nop 0
	v_cndmask_b32_e32 v56, v207, v56, vcc
	v_cmp_le_i32_e32 vcc, v194, v162
	v_add_u32_e32 v194, 0x50, v177
	s_nop 0
	v_cndmask_b32_e32 v57, v207, v57, vcc
	v_cmp_le_i32_e32 vcc, v194, v162
	v_add_u32_e32 v194, 0x51, v177
	s_nop 0
	v_cndmask_b32_e32 v58, v207, v58, vcc
	v_cmp_le_i32_e32 vcc, v194, v162
	v_add_u32_e32 v194, 0x52, v177
	s_nop 0
	v_cndmask_b32_e32 v59, v207, v59, vcc
	v_cmp_le_i32_e32 vcc, v194, v162
	v_add_u32_e32 v194, 0x53, v177
	s_nop 0
	v_cndmask_b32_e32 v60, v207, v60, vcc
	v_cmp_le_i32_e32 vcc, v194, v162
	v_add_u32_e32 v194, 0x54, v177
	s_nop 0
	v_cndmask_b32_e32 v61, v207, v61, vcc
	v_cmp_le_i32_e32 vcc, v194, v162
	v_add_u32_e32 v194, 0x55, v177
	s_nop 0
	v_cndmask_b32_e32 v62, v207, v62, vcc
	v_cmp_le_i32_e32 vcc, v194, v162
	v_add_u32_e32 v194, 0x56, v177
	s_nop 0
	v_cndmask_b32_e32 v63, v207, v63, vcc
	v_cmp_le_i32_e32 vcc, v194, v162
	v_add_u32_e32 v194, 0x57, v177
	s_nop 0
	v_cndmask_b32_e32 v64, v207, v64, vcc
	v_cmp_le_i32_e32 vcc, v194, v162
	v_add_u32_e32 v194, 0x60, v177
	s_nop 0
	v_cndmask_b32_e32 v65, v207, v65, vcc
	v_cmp_le_i32_e32 vcc, v194, v162
	v_add_u32_e32 v194, 0x61, v177
	s_nop 0
	v_cndmask_b32_e32 v34, v207, v34, vcc
	v_cmp_le_i32_e32 vcc, v194, v162
	v_add_u32_e32 v194, 0x62, v177
	s_nop 0
	v_cndmask_b32_e32 v35, v207, v35, vcc
	v_cmp_le_i32_e32 vcc, v194, v162
	v_add_u32_e32 v194, 0x63, v177
	s_nop 0
	v_cndmask_b32_e32 v36, v207, v36, vcc
	v_cmp_le_i32_e32 vcc, v194, v162
	v_add_u32_e32 v194, 0x64, v177
	s_nop 0
	v_cndmask_b32_e32 v37, v207, v37, vcc
	v_cmp_le_i32_e32 vcc, v194, v162
	v_add_u32_e32 v194, 0x65, v177
	s_nop 0
	v_cndmask_b32_e32 v38, v207, v38, vcc
	v_cmp_le_i32_e32 vcc, v194, v162
	v_add_u32_e32 v194, 0x66, v177
	s_nop 0
	v_cndmask_b32_e32 v39, v207, v39, vcc
	v_cmp_le_i32_e32 vcc, v194, v162
	v_add_u32_e32 v194, 0x67, v177
	s_nop 0
	v_cndmask_b32_e32 v40, v207, v40, vcc
	v_cmp_le_i32_e32 vcc, v194, v162
	v_add_u32_e32 v194, 0x70, v177
	s_nop 0
	v_cndmask_b32_e32 v41, v207, v41, vcc
	v_cmp_le_i32_e32 vcc, v194, v162
	v_add_u32_e32 v194, 0x71, v177
	s_nop 0
	v_cndmask_b32_e32 v42, v207, v42, vcc
	v_cmp_le_i32_e32 vcc, v194, v162
	v_add_u32_e32 v194, 0x72, v177
	s_nop 0
	v_cndmask_b32_e32 v43, v207, v43, vcc
	v_cmp_le_i32_e32 vcc, v194, v162
	v_add_u32_e32 v194, 0x73, v177
	s_nop 0
	v_cndmask_b32_e32 v44, v207, v44, vcc
	v_cmp_le_i32_e32 vcc, v194, v162
	v_add_u32_e32 v194, 0x74, v177
	s_nop 0
	v_cndmask_b32_e32 v45, v207, v45, vcc
	v_cmp_le_i32_e32 vcc, v194, v162
	v_add_u32_e32 v194, 0x75, v177
	s_nop 0
	v_cndmask_b32_e32 v46, v207, v46, vcc
	v_cmp_le_i32_e32 vcc, v194, v162
	v_add_u32_e32 v194, 0x76, v177
	v_add_u32_e32 v177, 0x77, v177
	v_cndmask_b32_e32 v47, v207, v47, vcc
	v_cmp_le_i32_e32 vcc, v194, v162
	s_nop 1
	v_cndmask_b32_e32 v48, v207, v48, vcc
	v_cmp_le_i32_e32 vcc, v177, v162
	s_nop 1
	v_cndmask_b32_e32 v49, v207, v49, vcc

.LBB0_280:
	s_or_b64 exec, exec, s[40:41]
	v_cndmask_b32_e64 v34, 0, 1, s[42:43]
	s_mov_b64 s[44:45], exec
	v_cmp_ne_u32_e32 vcc, 0, v34
	s_and_saveexec_b64 s[40:41], s[6:7]
	s_cmp_eq_u64 vcc, s[44:45]
	s_cselect_b64 s[42:43], -1, 0
	v_cndmask_b32_e64 v34, 0, 1, s[42:43]
	v_mov_b32_e32 v35, s46
	ds_write_b32 v35, v34 offset:32
	s_or_b64 exec, exec, s[40:41]
	v_cmp_lt_i32_e32 vcc, 0, v0
	s_and_saveexec_b64 s[40:41], vcc
	s_cbranch_execz .LBB0_284
	s_waitcnt vmcnt(2)
	v_mul_f64 v[178:179], v[246:247], s[28:29]
	v_add_f64 v[34:35], v[170:171], -v[178:179]
	v_cvt_f32_f64_e32 v0, v[34:35]
	v_add_f64 v[34:35], v[172:173], -v[178:179]
	ds_write_b128 v205, v[130:133]
	ds_write_b128 v205, v[134:137] offset:9216
	s_waitcnt vmcnt(1)
	ds_write_b128 v206, v[138:141] offset:18432
	s_waitcnt vmcnt(0)
	ds_write_b128 v206, v[142:145] offset:27136
	ds_write_b32 v161, v0 offset:35840
	v_cvt_f32_f64_e32 v0, v[34:35]
	ds_write_b32 v163, v0 offset:35840

; DI_ void ssm_conv_tile(int tile, const unsigned char* buf, unsigned char* obuf, const float* cw, const float* cbias, bf16_t* xsT, bf16_t* Btok, bf16_t* BT, bf16_t* Ctok, int tid) {
;     const int ct = tile & 63, tt = tile >> 6, ch0 = ct * 64, tb = tt * 128;
;     const int ch = tid & 63, run = tid >> 6, tl0 = run * 16, chg = ch0 + ch;
;     const float w0 = cw[chg], w1 = cw[4096 + chg], w2 = cw[2 * 4096 + chg], w3 = cw[3 * 4096 + chg], bb = cbias[chg];
.LBB0_559:
	s_and_b32 s8, s26, 0xfc0
	v_or_b32_e32 v234, s8, v25
	v_lshlrev_b32_e32 v236, 2, v234
	v_mov_b32_e32 v237, v48
	v_lshl_add_u64 v[238:239], s[68:69], 0, v[236:237]
	global_load_dword v242, v236, s[68:69]
	global_load_dword v246, v236, s[70:71]
	v_add_co_u32_e32 v240, vcc, 0x4000, v238
	s_nop 1
	v_addc_co_u32_e32 v241, vcc, 0, v239, vcc
	global_load_dword v243, v[240:241], off
	v_add_co_u32_e32 v240, vcc, 0x8000, v238
	s_nop 1
	v_addc_co_u32_e32 v241, vcc, 0, v239, vcc
	global_load_dword v244, v[240:241], off
	v_add_co_u32_e32 v240, vcc, 0xc000, v238
	s_nop 1
	v_addc_co_u32_e32 v241, vcc, 0, v239, vcc
	global_load_dword v245, v[240:241], off
	s_waitcnt vmcnt(0)
	v_readlane_b32 s0, v252, 61
	s_add_i32 s28, s29, s0
	s_cmpk_lt_i32 s28, 0x2000
	s_cselect_b64 s[6:7], -1, 0
	s_cmpk_gt_i32 s28, 0x1fff
	s_cselect_b64 s[0:1], -1, 0
	s_and_b64 vcc, exec, s[0:1]
	s_cbranch_vccnz .LBB0_565
	v_readlane_b32 s4, v254, 10
	s_add_i32 s4, s4, s26
	s_and_b32 s4, s4, 0xfc0
	s_lshl_b32 s8, s4, 1
	v_readlane_b32 s4, v254, 9
	s_add_i32 s4, s4, s27
	s_and_b32 s4, s4, 0xffffff80
	v_mov_b32_e32 v49, v48
	s_waitcnt vmcnt(0)
	v_add_u32_e32 v10, s4, v31
	v_mov_b32_e32 v50, v48
	v_mov_b32_e32 v51, v48
	v_mov_b64_e32 v[0:1], v[48:49]
	v_lshl_add_u64 v[8:9], v[28:29], 0, s[8:9]
	v_cmp_lt_i32_e32 vcc, 2, v10
	v_mov_b64_e32 v[2:3], v[50:51]
	s_and_saveexec_b64 s[10:11], vcc
	s_cbranch_execz .LBB0_562
	v_add_u32_e32 v0, -3, v10
	v_mov_b32_e32 v1, v48
	v_lshlrev_b64 v[0:1], 13, v[0:1]
	v_lshl_add_u64 v[0:1], v[8:9], 0, v[0:1]
	global_load_dwordx4 v[0:3], v[0:1], off

; DI_ float silu_f(float v) { return v / (1.f + __expf(-v)); }
; DI_ void ssm_conv_tile(int tile, const unsigned char* buf, unsigned char* obuf, const float* cw, const float* cbias, bf16_t* xsT, bf16_t* Btok, bf16_t* BT, bf16_t* Ctok, int tid) {
;     ...
;     const float w0 = cw[chg], w1 = cw[4096 + chg], w2 = cw[2 * 4096 + chg], w3 = cw[3 * 4096 + chg], bb = cbias[chg];
;     const bf16_t* col = (const bf16_t*)buf + ch;
;     float x0 = __uint_as_float((unsigned)col[(tl0 + 0) * 64] << 16), x1 = __uint_as_float((unsigned)col[(tl0 + 1) * 64] << 16), x2 = __uint_as_float((unsigned)col[(tl0 + 2) * 64] << 16);
;     float y[16];
; #pragma unroll
;     for (int i = 0; i < 16; ++i) { const float x3 = __uint_as_float((unsigned)col[(tl0 + 3 + i) * 64] << 16); const float v = bb + w0 * x0 + w1 * x1 + w2 * x2 + w3 * x3; y[i] = silu_f(v); x0 = x1; x1 = x2; x2 = x3; }
.LBB0_565:
	s_and_b32 s8, s26, 0xfc0
	v_mov_b32_e32 v36, v242
	s_nop 0
	v_mov_b32_e32 v38, v243
	s_cmpk_lt_u32 s8, 0xc00
	s_nop 0
	v_mov_b32_e32 v40, v244
	s_nop 0
	v_mov_b32_e32 v42, v245
	v_mov_b32_e32 v44, v246
	ds_read_u16 v37, v39 offset:1792
	ds_read_u16 v49, v39 offset:2048
	ds_read_u16 v47, v43
	s_cselect_b64 s[10:11], -1, 0
	s_cmpk_gt_u32 s8, 0xbff
	s_waitcnt lgkmcnt(2)
	v_lshlrev_b32_e32 v46, 16, v37
	s_waitcnt lgkmcnt(1)
	v_lshlrev_b32_e32 v51, 16, v49
	ds_read_u16 v37, v39 offset:2176
	ds_read_u16 v49, v39 offset:2304
	s_waitcnt lgkmcnt(2)
	v_lshlrev_b32_e32 v47, 16, v47
	v_mov_b32_e32 v50, v47
	v_mov_b32_e32 v54, v51
	s_waitcnt lgkmcnt(1)
	v_lshlrev_b32_e32 v55, 16, v37
	s_waitcnt lgkmcnt(0)
	v_lshlrev_b32_e32 v53, 16, v49
	ds_read_u16 v37, v39 offset:1536
	ds_read_u16 v49, v39 offset:1664
	s_waitcnt lgkmcnt(1)
	v_lshlrev_b32_e32 v58, 16, v37
	s_waitcnt lgkmcnt(0)
	v_lshlrev_b32_e32 v59, 16, v49
	v_pk_fma_f32 v[56:57], v[36:37], v[58:59], v[44:45] op_sel_hi:[0,1,0]
	ds_read_u16 v37, v39 offset:1280
	ds_read_u16 v49, v39 offset:1408
	s_waitcnt lgkmcnt(1)
	v_lshlrev_b32_e32 v62, 16, v37
	s_waitcnt lgkmcnt(0)
	v_lshlrev_b32_e32 v63, 16, v49
	v_pk_fma_f32 v[60:61], v[36:37], v[62:63], v[44:45] op_sel_hi:[0,1,0]
	ds_read_u16 v37, v39 offset:1024
	ds_read_u16 v49, v39 offset:1152
	s_waitcnt lgkmcnt(1)
	v_lshlrev_b32_e32 v66, 16, v37
	s_waitcnt lgkmcnt(0)
	v_lshlrev_b32_e32 v67, 16, v49
	v_pk_fma_f32 v[64:65], v[36:37], v[66:67], v[44:45] op_sel_hi:[0,1,0]
	ds_read_u16 v37, v39 offset:768
	ds_read_u16 v49, v39 offset:896
	s_waitcnt lgkmcnt(1)
	v_lshlrev_b32_e32 v70, 16, v37
	s_waitcnt lgkmcnt(0)
	v_lshlrev_b32_e32 v71, 16, v49
	v_pk_fma_f32 v[68:69], v[36:37], v[70:71], v[44:45] op_sel_hi:[0,1,0]
	ds_read_u16 v37, v39 offset:512
	ds_read_u16 v49, v39 offset:640
	s_waitcnt lgkmcnt(1)
	v_lshlrev_b32_e32 v74, 16, v37
	s_waitcnt lgkmcnt(0)
	v_lshlrev_b32_e32 v75, 16, v49
	v_pk_fma_f32 v[72:73], v[36:37], v[74:75], v[44:45] op_sel_hi:[0,1,0]
	ds_read_u16 v37, v39 offset:256
	ds_read_u16 v49, v39 offset:384
	s_waitcnt lgkmcnt(1)
	v_lshlrev_b32_e32 v88, 16, v37
	s_waitcnt lgkmcnt(0)
	v_lshlrev_b32_e32 v89, 16, v49
	v_pk_fma_f32 v[76:77], v[36:37], v[88:89], v[44:45] op_sel_hi:[0,1,0]
	ds_read_u16 v37, v39
	ds_read_u16 v49, v39 offset:128
	v_pk_mov_b32 v[94:95], v[88:89], v[74:75] op_sel:[1,0]
	s_waitcnt lgkmcnt(1)
	v_lshlrev_b32_e32 v90, 16, v37
	s_waitcnt lgkmcnt(0)
; DI_ unsigned pk2(float lo, float hi) { typedef float f2 __attribute__((ext_vector_type(2))); typedef __bf16 b2 __attribute__((ext_vector_type(2))); f2 v = {lo, hi}; b2 b = __builtin_convertvector(v, b2); return __builtin_bit_cast(unsigned, b); }
; DI_ float silu_f(float v) { return v / (1.f + __expf(-v)); }
; DI_ void ssm_conv_tile(int tile, const unsigned char* buf, unsigned char* obuf, const float* cw, const float* cbias, bf16_t* xsT, bf16_t* Btok, bf16_t* BT, bf16_t* Ctok, int tid) {
;     ...
;     for (int i = 0; i < 16; ++i) { const float x3 = __uint_as_float((unsigned)col[(tl0 + 3 + i) * 64] << 16); const float v = bb + w0 * x0 + w1 * x1 + w2 * x2 + w3 * x3; y[i] = silu_f(v); x0 = x1; x1 = x2; x2 = x3; }
;     u32x4 o0, o1; o0.x = pk2(y[0], y[1]); o0.y = pk2(y[2], y[3]); o0.z = pk2(y[4], y[5]); o0.w = pk2(y[6], y[7]); o1.x = pk2(y[8], y[9]); o1.y = pk2(y[10], y[11]); o1.z = pk2(y[12], y[13]); o1.w = pk2(y[14], y[15]);
;     const int tg0 = tb + tl0;
;     unsigned char* obuf2 = obuf + 16384;
;     const bool chmaj = ch0 < 3072, tokmaj = ch0 >= 2048;
;     if (chmaj) { *(u32x4*)(obuf2 + ch * 272 + tl0 * 2) = o0; *(u32x4*)(obuf2 + ch * 272 + tl0 * 2 + 16) = o1; }
	v_lshlrev_b32_e32 v91, 16, v49
	v_pk_fma_f32 v[92:93], v[36:37], v[90:91], v[44:45] op_sel_hi:[0,1,0]
	v_pk_mov_b32 v[90:91], v[90:91], v[88:89] op_sel:[1,0]
	v_pk_fma_f32 v[76:77], v[38:39], v[94:95], v[76:77] op_sel_hi:[0,1,1]
	v_pk_fma_f32 v[90:91], v[38:39], v[90:91], v[92:93] op_sel_hi:[0,1,1]
	v_pk_fma_f32 v[88:89], v[40:41], v[88:89], v[90:91] op_sel_hi:[0,1,1]
	v_pk_fma_f32 v[88:89], v[42:43], v[94:95], v[88:89] op_sel_hi:[0,1,1]
	v_mul_f32_e32 v37, 0xbfb8aa3b, v88
	v_exp_f32_e32 v90, v37
	v_mul_f32_e32 v37, 0xbfb8aa3b, v89
	v_exp_f32_e32 v91, v37
	s_nop 0
	v_pk_add_f32 v[90:91], v[90:91], 1.0 op_sel_hi:[1,0]
	s_nop 0
	v_rcp_f32_e32 v49, v91
	s_nop 0
	v_mul_f32_e32 v87, v89, v49
	v_mov_b32_e32 v37, v87
	v_rcp_f32_e32 v52, v90
	v_mov_b32_e32 v37, v37
	v_mul_f32_e32 v89, v88, v52
	v_mov_b32_e32 v49, v89
	v_pk_mov_b32 v[88:89], v[74:75], v[70:71] op_sel:[1,0]
	v_pk_fma_f32 v[74:75], v[40:41], v[74:75], v[76:77] op_sel_hi:[0,1,1]
	v_pk_fma_f32 v[76:77], v[42:43], v[88:89], v[74:75] op_sel_hi:[0,1,1]
	v_mul_f32_e32 v52, 0xbfb8aa3b, v76
	v_exp_f32_e32 v74, v52
	v_mul_f32_e32 v52, 0xbfb8aa3b, v77
	v_exp_f32_e32 v75, v52
	v_pk_fma_f32 v[72:73], v[38:39], v[88:89], v[72:73] op_sel_hi:[0,1,1]
	v_pk_add_f32 v[90:91], v[74:75], 1.0 op_sel_hi:[1,0]
	s_nop 0
	v_rcp_f32_e32 v74, v91
	s_nop 0
	v_mul_f32_e32 v87, v77, v74
	v_mov_b32_e32 v74, v87
	v_rcp_f32_e32 v75, v90
	s_nop 0
	v_mul_f32_e32 v87, v76, v75
	v_mov_b32_e32 v75, v87
	v_pk_mov_b32 v[76:77], v[70:71], v[66:67] op_sel:[1,0]
	v_pk_fma_f32 v[70:71], v[40:41], v[70:71], v[72:73] op_sel_hi:[0,1,1]
	v_pk_fma_f32 v[72:73], v[42:43], v[76:77], v[70:71] op_sel_hi:[0,1,1]
	v_mul_f32_e32 v52, 0xbfb8aa3b, v72
	v_exp_f32_e32 v70, v52
	v_mul_f32_e32 v52, 0xbfb8aa3b, v73
	v_exp_f32_e32 v71, v52
	v_pk_fma_f32 v[68:69], v[38:39], v[76:77], v[68:69] op_sel_hi:[0,1,1]
	v_pk_add_f32 v[88:89], v[70:71], 1.0 op_sel_hi:[1,0]
	s_nop 0
	v_rcp_f32_e32 v70, v89
	s_nop 0
	v_mul_f32_e32 v87, v73, v70
	v_mov_b32_e32 v70, v87
	v_rcp_f32_e32 v71, v88
	s_nop 0
	v_mul_f32_e32 v87, v72, v71
	v_mov_b32_e32 v71, v87
	v_pk_mov_b32 v[72:73], v[66:67], v[62:63] op_sel:[1,0]
	v_pk_fma_f32 v[66:67], v[40:41], v[66:67], v[68:69] op_sel_hi:[0,1,1]
	v_pk_fma_f32 v[68:69], v[42:43], v[72:73], v[66:67] op_sel_hi:[0,1,1]
	v_mul_f32_e32 v52, 0xbfb8aa3b, v68
	v_exp_f32_e32 v66, v52
	v_mul_f32_e32 v52, 0xbfb8aa3b, v69
	v_exp_f32_e32 v67, v52
	v_pk_fma_f32 v[64:65], v[38:39], v[72:73], v[64:65] op_sel_hi:[0,1,1]
	v_pk_add_f32 v[76:77], v[66:67], 1.0 op_sel_hi:[1,0]
	s_nop 0
	v_rcp_f32_e32 v66, v77
	s_nop 0
	v_mul_f32_e32 v87, v69, v66
	v_mov_b32_e32 v66, v87
	v_rcp_f32_e32 v67, v76
	s_nop 0
	v_mul_f32_e32 v77, v68, v67
	v_mov_b32_e32 v67, v77
	v_pk_mov_b32 v[68:69], v[62:63], v[58:59] op_sel:[1,0]
	v_pk_fma_f32 v[62:63], v[40:41], v[62:63], v[64:65] op_sel_hi:[0,1,1]
	v_pk_fma_f32 v[64:65], v[42:43], v[68:69], v[62:63] op_sel_hi:[0,1,1]
	v_mul_f32_e32 v52, 0xbfb8aa3b, v64
	v_exp_f32_e32 v62, v52
	v_mul_f32_e32 v52, 0xbfb8aa3b, v65
	v_exp_f32_e32 v63, v52
	v_pk_fma_f32 v[60:61], v[38:39], v[68:69], v[60:61] op_sel_hi:[0,1,1]
	v_pk_add_f32 v[72:73], v[62:63], 1.0 op_sel_hi:[1,0]
	s_nop 0
	v_rcp_f32_e32 v62, v73
	s_nop 0
	v_mul_f32_e32 v76, v65, v62
	v_mov_b32_e32 v62, v76
	v_rcp_f32_e32 v63, v72
	s_nop 0
	v_mul_f32_e32 v73, v64, v63
	v_mov_b32_e32 v63, v73
	v_pk_mov_b32 v[64:65], v[58:59], v[46:47] op_sel:[1,0]
	v_pk_fma_f32 v[58:59], v[40:41], v[58:59], v[60:61] op_sel_hi:[0,1,1]
	v_pk_fma_f32 v[60:61], v[42:43], v[64:65], v[58:59] op_sel_hi:[0,1,1]
	v_mul_f32_e32 v52, 0xbfb8aa3b, v60
	v_exp_f32_e32 v58, v52
	v_mul_f32_e32 v52, 0xbfb8aa3b, v61
	v_exp_f32_e32 v59, v52
	v_pk_fma_f32 v[56:57], v[38:39], v[64:65], v[56:57] op_sel_hi:[0,1,1]
	v_pk_fma_f32 v[56:57], v[40:41], v[46:47], v[56:57] op_sel_hi:[0,1,1]
	v_pk_fma_f32 v[46:47], v[36:37], v[46:47], v[44:45] op_sel_hi:[0,1,0]
	v_pk_add_f32 v[68:69], v[58:59], 1.0 op_sel_hi:[1,0]
	v_pk_fma_f32 v[46:47], v[38:39], v[50:51], v[46:47] op_sel_hi:[0,1,1]
	v_rcp_f32_e32 v58, v69
	v_pk_fma_f32 v[46:47], v[40:41], v[54:55], v[46:47] op_sel_hi:[0,1,1]
	v_mul_f32_e32 v72, v61, v58
	v_mov_b32_e32 v58, v72
	v_rcp_f32_e32 v59, v68
	s_nop 0
	v_mul_f32_e32 v69, v60, v59
	v_mov_b32_e32 v59, v69
	v_pk_fma_f32 v[60:61], v[42:43], v[50:51], v[56:57] op_sel_hi:[0,1,1]
	v_mul_f32_e32 v52, 0xbfb8aa3b, v60
	v_exp_f32_e32 v56, v52
	v_mul_f32_e32 v52, 0xbfb8aa3b, v61
	v_exp_f32_e32 v57, v52
	s_nop 0
	v_pk_add_f32 v[64:65], v[56:57], 1.0 op_sel_hi:[1,0]
	s_nop 0
	v_rcp_f32_e32 v56, v65
	s_nop 0
	v_mul_f32_e32 v68, v61, v56
	v_mov_b32_e32 v56, v68
	v_rcp_f32_e32 v57, v64
	s_nop 0
	v_mul_f32_e32 v65, v60, v57
	v_mov_b32_e32 v57, v65
	v_mov_b32_e32 v52, v55
	v_pk_fma_f32 v[46:47], v[42:43], v[52:53], v[46:47] op_sel_hi:[0,1,1]
	v_mul_f32_e32 v36, 0xbfb8aa3b, v46
	v_exp_f32_e32 v50, v36
	v_mul_f32_e32 v36, 0xbfb8aa3b, v47
	v_exp_f32_e32 v51, v36
	s_nop 0
	v_pk_add_f32 v[50:51], v[50:51], 1.0 op_sel_hi:[1,0]
	s_nop 0
	v_rcp_f32_e32 v38, v51
	s_nop 0
	v_mul_f32_e32 v42, v47, v38
	v_mov_b32_e32 v36, v42
	v_rcp_f32_e32 v40, v50
	v_mov_b32_e32 v36, v36
	v_mul_f32_e32 v44, v46, v40
	v_mov_b32_e32 v38, v44
	s_cbranch_scc1 .LBB0_567
	v_cvt_pk_bf16_f32 v50, v49, v37
	v_cvt_pk_bf16_f32 v51, v75, v74
	v_cvt_pk_bf16_f32 v52, v71, v70
	v_cvt_pk_bf16_f32 v53, v67, v66
	v_add_u32_e32 v40, v45, v78
	v_cvt_pk_bf16_f32 v88, v63, v62
	v_cvt_pk_bf16_f32 v89, v59, v58
	v_cvt_pk_bf16_f32 v90, v57, v56
	v_cvt_pk_bf16_f32 v91, v38, v36
	ds_write_b128 v40, v[50:53] offset:49920
	ds_write_b128 v40, v[88:91] offset:49936

; #define SC_WRITE(R0, R1, R2, buf_) do { unsigned char* d_ = lds + (buf_) * SC_BUF + row0 * 128 + chunk * 16; *(u32x4*)d_ = R0; *(u32x4*)(d_ + 64 * 128) = R1; if (tid < 24) *(u32x4*)(d_ + 128 * 128) = R2; } while (0)
; DI_ void ssm_conv_tile(int tile, const unsigned char* buf, unsigned char* obuf, const float* cw, const float* cbias, bf16_t* xsT, bf16_t* Btok, bf16_t* BT, bf16_t* Ctok, int tid) {
;     ...
;     const float w0 = cw[chg], w1 = cw[4096 + chg], w2 = cw[2 * 4096 + chg], w3 = cw[3 * 4096 + chg], bb = cbias[chg];
; DI_ void ssm_conv_phase(const bf16_t* raw, const float* cw  , const float* cbias, bf16_t* xsT, bf16_t* Btok, bf16_t* BT, bf16_t* Ctok, unsigned char* lds, int tid) {
;     ...
;     for (; tile < NTILE; tile += 2 * G) {
;         SC_LOAD(a0, a1, a2, tile + 2 * G);
;         ssm_conv_tile(tile, lds, lds + 2 * SC_BUF, cw, cbias, xsT, Btok, BT, Ctok, tid);
;         if (tile + G < NTILE) SC_WRITE(b0, b1, b2, 1);
;         __syncthreads();
;         if (tile + G >= NTILE) break;
;         SC_LOAD(b0, b1, b2, tile + 3 * G);
;         ssm_conv_tile(tile + G, lds + SC_BUF, lds + 2 * SC_BUF, cw, cbias, xsT, Btok, BT, Ctok, tid);
.LBB0_581:
	s_cmpk_gt_i32 s4, 0x1fff
	s_mov_b64 s[10:11], -1
	s_waitcnt lgkmcnt(0)
	s_barrier
	s_cbranch_scc1 .LBB0_558
	v_readlane_b32 s4, v254, 11
	s_add_i32 s4, s4, s26
	s_and_b32 s8, s4, 0xfc0
	v_or_b32_e32 v234, s8, v25
	v_lshlrev_b32_e32 v236, 2, v234
	v_mov_b32_e32 v237, v48
	v_lshl_add_u64 v[238:239], s[68:69], 0, v[236:237]
	global_load_dword v242, v236, s[68:69]
	global_load_dword v246, v236, s[70:71]
	v_add_co_u32_e32 v240, vcc, 0x4000, v238
	s_nop 1
	v_addc_co_u32_e32 v241, vcc, 0, v239, vcc
	global_load_dword v243, v[240:241], off
	v_add_co_u32_e32 v240, vcc, 0x8000, v238
	s_nop 1
	v_addc_co_u32_e32 v241, vcc, 0, v239, vcc
	global_load_dword v244, v[240:241], off
	v_add_co_u32_e32 v240, vcc, 0xc000, v238
	s_nop 1
	v_addc_co_u32_e32 v241, vcc, 0, v239, vcc
	global_load_dword v245, v[240:241], off
	s_waitcnt vmcnt(0)
	s_mul_i32 s4, s92, 3
	s_add_i32 s4, s4, s29
	s_cmpk_gt_i32 s4, 0x1fff
	s_cbranch_scc1 .LBB0_588
	s_mul_i32 s4, s92, 0xc0
	s_add_i32 s4, s4, s26
	s_and_b32 s4, s4, 0xfc0
	s_lshl_b32 s8, s4, 1
	s_mul_i32 s4, s92, 6
	s_add_i32 s4, s4, s27
	s_and_b32 s4, s4, 0xffffff80
	v_mov_b32_e32 v49, v48
	v_add_u32_e32 v22, s4, v31
	v_mov_b32_e32 v50, v48
	v_mov_b32_e32 v51, v48
	v_mov_b64_e32 v[12:13], v[48:49]
	v_lshl_add_u64 v[20:21], v[28:29], 0, s[8:9]
	v_cmp_lt_i32_e32 vcc, 2, v22
	v_mov_b64_e32 v[14:15], v[50:51]
	s_and_saveexec_b64 s[10:11], vcc
	s_cbranch_execz .LBB0_585
	v_add_u32_e32 v12, -3, v22
	v_mov_b32_e32 v13, v48
	v_lshlrev_b64 v[12:13], 13, v[12:13]
	v_lshl_add_u64 v[12:13], v[20:21], 0, v[12:13]
	global_load_dwordx4 v[12:15], v[12:13], off

; DI_ float silu_f(float v) { return v / (1.f + __expf(-v)); }
; DI_ void ssm_conv_tile(int tile, const unsigned char* buf, unsigned char* obuf, const float* cw, const float* cbias, bf16_t* xsT, bf16_t* Btok, bf16_t* BT, bf16_t* Ctok, int tid) {
;     ...
;     const float w0 = cw[chg], w1 = cw[4096 + chg], w2 = cw[2 * 4096 + chg], w3 = cw[3 * 4096 + chg], bb = cbias[chg];
;     const bf16_t* col = (const bf16_t*)buf + ch;
;     float x0 = __uint_as_float((unsigned)col[(tl0 + 0) * 64] << 16), x1 = __uint_as_float((unsigned)col[(tl0 + 1) * 64] << 16), x2 = __uint_as_float((unsigned)col[(tl0 + 2) * 64] << 16);
;     float y[16];
; #pragma unroll
;     for (int i = 0; i < 16; ++i) { const float x3 = __uint_as_float((unsigned)col[(tl0 + 3 + i) * 64] << 16); const float v = bb + w0 * x0 + w1 * x1 + w2 * x2 + w3 * x3; y[i] = silu_f(v); x0 = x1; x1 = x2; x2 = x3; }
.LBB0_588:
	v_readlane_b32 s4, v254, 11
	s_add_i32 s4, s4, s26
	s_and_b32 s8, s4, 0xfc0
	v_mov_b32_e32 v36, v242
	s_nop 0
	v_mov_b32_e32 v38, v243
	s_cmpk_lt_u32 s8, 0xc00
	s_nop 0
	v_mov_b32_e32 v40, v244
	s_nop 0
	v_mov_b32_e32 v42, v245
	v_mov_b32_e32 v44, v246
	ds_read_u16 v37, v39 offset:18560
	ds_read_u16 v46, v43 offset:16768
	s_cselect_b64 s[10:11], -1, 0
	s_cmpk_gt_u32 s8, 0xbff
	s_waitcnt lgkmcnt(0)
	v_lshlrev_b32_e32 v47, 16, v46
	v_lshlrev_b32_e32 v46, 16, v37
	ds_read_u16 v37, v39 offset:18816
	v_mov_b32_e32 v50, v47
	s_waitcnt lgkmcnt(0)
	v_lshlrev_b32_e32 v51, 16, v37
	ds_read_u16 v37, v39 offset:18944
	ds_read_u16 v49, v39 offset:19072
	v_mov_b32_e32 v54, v51
	s_waitcnt lgkmcnt(1)
	v_lshlrev_b32_e32 v55, 16, v37
	s_waitcnt lgkmcnt(0)
	v_lshlrev_b32_e32 v53, 16, v49
	ds_read_u16 v37, v39 offset:18304
	ds_read_u16 v49, v39 offset:18432
	s_waitcnt lgkmcnt(1)
	v_lshlrev_b32_e32 v58, 16, v37
	s_waitcnt lgkmcnt(0)
	v_lshlrev_b32_e32 v59, 16, v49
	v_pk_fma_f32 v[56:57], v[36:37], v[58:59], v[44:45] op_sel_hi:[0,1,0]
	ds_read_u16 v37, v39 offset:18048
	ds_read_u16 v49, v39 offset:18176
	s_waitcnt lgkmcnt(1)
	v_lshlrev_b32_e32 v62, 16, v37
	s_waitcnt lgkmcnt(0)
	v_lshlrev_b32_e32 v63, 16, v49
	v_pk_fma_f32 v[60:61], v[36:37], v[62:63], v[44:45] op_sel_hi:[0,1,0]
	ds_read_u16 v37, v39 offset:17792
	ds_read_u16 v49, v39 offset:17920
	s_waitcnt lgkmcnt(1)
	v_lshlrev_b32_e32 v66, 16, v37
	s_waitcnt lgkmcnt(0)
	v_lshlrev_b32_e32 v67, 16, v49
	v_pk_fma_f32 v[64:65], v[36:37], v[66:67], v[44:45] op_sel_hi:[0,1,0]
	ds_read_u16 v37, v39 offset:17536
	ds_read_u16 v49, v39 offset:17664
	s_waitcnt lgkmcnt(1)
	v_lshlrev_b32_e32 v70, 16, v37
	s_waitcnt lgkmcnt(0)
	v_lshlrev_b32_e32 v71, 16, v49
	v_pk_fma_f32 v[68:69], v[36:37], v[70:71], v[44:45] op_sel_hi:[0,1,0]
	ds_read_u16 v37, v39 offset:17280
	ds_read_u16 v49, v39 offset:17408
	s_waitcnt lgkmcnt(1)
	v_lshlrev_b32_e32 v74, 16, v37
	s_waitcnt lgkmcnt(0)
	v_lshlrev_b32_e32 v75, 16, v49
	v_pk_fma_f32 v[72:73], v[36:37], v[74:75], v[44:45] op_sel_hi:[0,1,0]
	ds_read_u16 v37, v39 offset:17024
	ds_read_u16 v49, v39 offset:17152
	s_waitcnt lgkmcnt(1)
	v_lshlrev_b32_e32 v88, 16, v37
	s_waitcnt lgkmcnt(0)
	v_lshlrev_b32_e32 v89, 16, v49
	v_pk_fma_f32 v[76:77], v[36:37], v[88:89], v[44:45] op_sel_hi:[0,1,0]
	ds_read_u16 v37, v39 offset:16768
	ds_read_u16 v49, v39 offset:16896
	v_pk_mov_b32 v[94:95], v[88:89], v[74:75] op_sel:[1,0]
	s_waitcnt lgkmcnt(1)
	v_lshlrev_b32_e32 v90, 16, v37
	s_waitcnt lgkmcnt(0)
; DI_ unsigned pk2(float lo, float hi) { typedef float f2 __attribute__((ext_vector_type(2))); typedef __bf16 b2 __attribute__((ext_vector_type(2))); f2 v = {lo, hi}; b2 b = __builtin_convertvector(v, b2); return __builtin_bit_cast(unsigned, b); }
; DI_ float silu_f(float v) { return v / (1.f + __expf(-v)); }
; DI_ void ssm_conv_tile(int tile, const unsigned char* buf, unsigned char* obuf, const float* cw, const float* cbias, bf16_t* xsT, bf16_t* Btok, bf16_t* BT, bf16_t* Ctok, int tid) {
;     ...
;     for (int i = 0; i < 16; ++i) { const float x3 = __uint_as_float((unsigned)col[(tl0 + 3 + i) * 64] << 16); const float v = bb + w0 * x0 + w1 * x1 + w2 * x2 + w3 * x3; y[i] = silu_f(v); x0 = x1; x1 = x2; x2 = x3; }
;     u32x4 o0, o1; o0.x = pk2(y[0], y[1]); o0.y = pk2(y[2], y[3]); o0.z = pk2(y[4], y[5]); o0.w = pk2(y[6], y[7]); o1.x = pk2(y[8], y[9]); o1.y = pk2(y[10], y[11]); o1.z = pk2(y[12], y[13]); o1.w = pk2(y[14], y[15]);
;     const int tg0 = tb + tl0;
;     unsigned char* obuf2 = obuf + 16384;
;     const bool chmaj = ch0 < 3072, tokmaj = ch0 >= 2048;
;     if (chmaj) { *(u32x4*)(obuf2 + ch * 272 + tl0 * 2) = o0; *(u32x4*)(obuf2 + ch * 272 + tl0 * 2 + 16) = o1; }
	v_lshlrev_b32_e32 v91, 16, v49
	v_pk_fma_f32 v[92:93], v[36:37], v[90:91], v[44:45] op_sel_hi:[0,1,0]
	v_pk_mov_b32 v[90:91], v[90:91], v[88:89] op_sel:[1,0]
	v_pk_fma_f32 v[76:77], v[38:39], v[94:95], v[76:77] op_sel_hi:[0,1,1]
	v_pk_fma_f32 v[90:91], v[38:39], v[90:91], v[92:93] op_sel_hi:[0,1,1]
	v_pk_fma_f32 v[88:89], v[40:41], v[88:89], v[90:91] op_sel_hi:[0,1,1]
	v_pk_fma_f32 v[88:89], v[42:43], v[94:95], v[88:89] op_sel_hi:[0,1,1]
	v_mul_f32_e32 v37, 0xbfb8aa3b, v88
	v_exp_f32_e32 v90, v37
	v_mul_f32_e32 v37, 0xbfb8aa3b, v89
	v_exp_f32_e32 v91, v37
	s_nop 0
	v_pk_add_f32 v[90:91], v[90:91], 1.0 op_sel_hi:[1,0]
	s_nop 0
	v_rcp_f32_e32 v49, v91
	s_nop 0
	v_mul_f32_e32 v87, v89, v49
	v_mov_b32_e32 v37, v87
	v_rcp_f32_e32 v52, v90
	v_mov_b32_e32 v37, v37
	v_mul_f32_e32 v89, v88, v52
	v_mov_b32_e32 v49, v89
	v_pk_mov_b32 v[88:89], v[74:75], v[70:71] op_sel:[1,0]
	v_pk_fma_f32 v[74:75], v[40:41], v[74:75], v[76:77] op_sel_hi:[0,1,1]
	v_pk_fma_f32 v[76:77], v[42:43], v[88:89], v[74:75] op_sel_hi:[0,1,1]
	v_mul_f32_e32 v52, 0xbfb8aa3b, v76
	v_exp_f32_e32 v74, v52
	v_mul_f32_e32 v52, 0xbfb8aa3b, v77
	v_exp_f32_e32 v75, v52
	v_pk_fma_f32 v[72:73], v[38:39], v[88:89], v[72:73] op_sel_hi:[0,1,1]
	v_pk_add_f32 v[90:91], v[74:75], 1.0 op_sel_hi:[1,0]
	s_nop 0
	v_rcp_f32_e32 v74, v91
	s_nop 0
	v_mul_f32_e32 v87, v77, v74
	v_mov_b32_e32 v74, v87
	v_rcp_f32_e32 v75, v90
	s_nop 0
	v_mul_f32_e32 v87, v76, v75
	v_mov_b32_e32 v75, v87
	v_pk_mov_b32 v[76:77], v[70:71], v[66:67] op_sel:[1,0]
	v_pk_fma_f32 v[70:71], v[40:41], v[70:71], v[72:73] op_sel_hi:[0,1,1]
	v_pk_fma_f32 v[72:73], v[42:43], v[76:77], v[70:71] op_sel_hi:[0,1,1]
	v_mul_f32_e32 v52, 0xbfb8aa3b, v72
	v_exp_f32_e32 v70, v52
	v_mul_f32_e32 v52, 0xbfb8aa3b, v73
	v_exp_f32_e32 v71, v52
	v_pk_fma_f32 v[68:69], v[38:39], v[76:77], v[68:69] op_sel_hi:[0,1,1]
	v_pk_add_f32 v[88:89], v[70:71], 1.0 op_sel_hi:[1,0]
	s_nop 0
	v_rcp_f32_e32 v70, v89
	s_nop 0
	v_mul_f32_e32 v87, v73, v70
	v_mov_b32_e32 v70, v87
	v_rcp_f32_e32 v71, v88
	s_nop 0
	v_mul_f32_e32 v87, v72, v71
	v_mov_b32_e32 v71, v87
	v_pk_mov_b32 v[72:73], v[66:67], v[62:63] op_sel:[1,0]
	v_pk_fma_f32 v[66:67], v[40:41], v[66:67], v[68:69] op_sel_hi:[0,1,1]
	v_pk_fma_f32 v[68:69], v[42:43], v[72:73], v[66:67] op_sel_hi:[0,1,1]
	v_mul_f32_e32 v52, 0xbfb8aa3b, v68
	v_exp_f32_e32 v66, v52
	v_mul_f32_e32 v52, 0xbfb8aa3b, v69
	v_exp_f32_e32 v67, v52
	v_pk_fma_f32 v[64:65], v[38:39], v[72:73], v[64:65] op_sel_hi:[0,1,1]
	v_pk_add_f32 v[76:77], v[66:67], 1.0 op_sel_hi:[1,0]
	s_nop 0
	v_rcp_f32_e32 v66, v77
	s_nop 0
	v_mul_f32_e32 v87, v69, v66
	v_mov_b32_e32 v66, v87
	v_rcp_f32_e32 v67, v76
	s_nop 0
	v_mul_f32_e32 v77, v68, v67
	v_mov_b32_e32 v67, v77
	v_pk_mov_b32 v[68:69], v[62:63], v[58:59] op_sel:[1,0]
	v_pk_fma_f32 v[62:63], v[40:41], v[62:63], v[64:65] op_sel_hi:[0,1,1]
	v_pk_fma_f32 v[64:65], v[42:43], v[68:69], v[62:63] op_sel_hi:[0,1,1]
	v_mul_f32_e32 v52, 0xbfb8aa3b, v64
	v_exp_f32_e32 v62, v52
	v_mul_f32_e32 v52, 0xbfb8aa3b, v65
	v_exp_f32_e32 v63, v52
	v_pk_fma_f32 v[60:61], v[38:39], v[68:69], v[60:61] op_sel_hi:[0,1,1]
	v_pk_add_f32 v[72:73], v[62:63], 1.0 op_sel_hi:[1,0]
	s_nop 0
	v_rcp_f32_e32 v62, v73
	s_nop 0
	v_mul_f32_e32 v76, v65, v62
	v_mov_b32_e32 v62, v76
	v_rcp_f32_e32 v63, v72
	s_nop 0
	v_mul_f32_e32 v73, v64, v63
	v_mov_b32_e32 v63, v73
	v_pk_mov_b32 v[64:65], v[58:59], v[46:47] op_sel:[1,0]
	v_pk_fma_f32 v[58:59], v[40:41], v[58:59], v[60:61] op_sel_hi:[0,1,1]
	v_pk_fma_f32 v[60:61], v[42:43], v[64:65], v[58:59] op_sel_hi:[0,1,1]
	v_mul_f32_e32 v52, 0xbfb8aa3b, v60
	v_exp_f32_e32 v58, v52
	v_mul_f32_e32 v52, 0xbfb8aa3b, v61
	v_exp_f32_e32 v59, v52
	v_pk_fma_f32 v[56:57], v[38:39], v[64:65], v[56:57] op_sel_hi:[0,1,1]
	v_pk_fma_f32 v[56:57], v[40:41], v[46:47], v[56:57] op_sel_hi:[0,1,1]
	v_pk_fma_f32 v[46:47], v[36:37], v[46:47], v[44:45] op_sel_hi:[0,1,0]
	v_pk_add_f32 v[68:69], v[58:59], 1.0 op_sel_hi:[1,0]
	v_pk_fma_f32 v[46:47], v[38:39], v[50:51], v[46:47] op_sel_hi:[0,1,1]
	v_rcp_f32_e32 v58, v69
	v_pk_fma_f32 v[46:47], v[40:41], v[54:55], v[46:47] op_sel_hi:[0,1,1]
	v_mul_f32_e32 v72, v61, v58
	v_mov_b32_e32 v58, v72
	v_rcp_f32_e32 v59, v68
	s_nop 0
	v_mul_f32_e32 v69, v60, v59
	v_mov_b32_e32 v59, v69
	v_pk_fma_f32 v[60:61], v[42:43], v[50:51], v[56:57] op_sel_hi:[0,1,1]
	v_mul_f32_e32 v52, 0xbfb8aa3b, v60
	v_exp_f32_e32 v56, v52
	v_mul_f32_e32 v52, 0xbfb8aa3b, v61
	v_exp_f32_e32 v57, v52
	s_nop 0
	v_pk_add_f32 v[64:65], v[56:57], 1.0 op_sel_hi:[1,0]
	s_nop 0
	v_rcp_f32_e32 v56, v65
	s_nop 0
	v_mul_f32_e32 v68, v61, v56
	v_mov_b32_e32 v56, v68
	v_rcp_f32_e32 v57, v64
	s_nop 0
	v_mul_f32_e32 v65, v60, v57
	v_mov_b32_e32 v57, v65
	v_mov_b32_e32 v52, v55
	v_pk_fma_f32 v[46:47], v[42:43], v[52:53], v[46:47] op_sel_hi:[0,1,1]
	v_mul_f32_e32 v36, 0xbfb8aa3b, v46
	v_exp_f32_e32 v50, v36
	v_mul_f32_e32 v36, 0xbfb8aa3b, v47
	v_exp_f32_e32 v51, v36
	s_nop 0
	v_pk_add_f32 v[50:51], v[50:51], 1.0 op_sel_hi:[1,0]
	s_nop 0
	v_rcp_f32_e32 v38, v51
	s_nop 0
	v_mul_f32_e32 v42, v47, v38
	v_mov_b32_e32 v36, v42
	v_rcp_f32_e32 v40, v50
	v_mov_b32_e32 v36, v36
	v_mul_f32_e32 v44, v46, v40
	v_mov_b32_e32 v38, v44
	s_cbranch_scc1 .LBB0_590
	v_cvt_pk_bf16_f32 v50, v49, v37
	v_cvt_pk_bf16_f32 v51, v75, v74
	v_cvt_pk_bf16_f32 v52, v71, v70
	v_cvt_pk_bf16_f32 v53, v67, v66
	v_add_u32_e32 v40, v45, v78
	v_cvt_pk_bf16_f32 v88, v63, v62
	v_cvt_pk_bf16_f32 v89, v59, v58
	v_cvt_pk_bf16_f32 v90, v57, v56
	v_cvt_pk_bf16_f32 v91, v38, v36
	ds_write_b128 v40, v[50:53] offset:49920
	ds_write_b128 v40, v[88:91] offset:49936

; DI_ float bf_lo(unsigned w) { return __uint_as_float(w << 16); }
; DI_ float bf_hi(unsigned w) { return __uint_as_float(w & 0xffff0000u); }
; DI_ bf16x8 pack8(float a0, float a1, float a2, float a3, float a4, float a5, float a6, float a7) { u32x4 p; p.x = pk2(a0, a1); p.y = pk2(a2, a3); p.z = pk2(a4, a5); p.w = pk2(a6, a7); return __builtin_bit_cast(bf16x8, p); }
; DI_ void ssd_passA(const bf16_t* xsT, const bf16_t* BT, const float* dt, const float* acum, bf16_t* Sc, unsigned char* lds, int tid, int lane, int wid) {
;     ...
;             const int pblk = ph & 1, h2 = ph >> 1;
;             bf16x8 xa[8];
;             {
;                 const bf16_t* xp = xsT + (size_t)((hA + h2) * 64 + 32 * pblk + r32) * XP + t0 + 8 * hi; const float* wp = wl + (2 * wid + h2) * 128 + 8 * hi;
; #pragma unroll
;                 for (int ks = 0; ks < 8; ++ks) { const u32x4 xw = *(const u32x4*)(xp + 16 * ks); const f32x4 wa = *(const f32x4*)(wp + 16 * ks), wb = *(const f32x4*)(wp + 16 * ks + 4);
;                     xa[ks] = pack8(bf_lo(xw.x) * wa[0], bf_hi(xw.x) * wa[1], bf_lo(xw.y) * wa[2], bf_hi(xw.y) * wa[3], bf_lo(xw.z) * wb[0], bf_hi(xw.z) * wb[1], bf_lo(xw.w) * wb[2], bf_hi(xw.w) * wb[3]); }
;             }
.LBB0_655:
	s_lshr_b32 s4, s27, 1
	s_add_i32 s0, s26, s4
	s_ashr_i32 s1, s0, 31
	v_cndmask_b32_e64 v0, 0, 1, s[6:7]
	s_lshl_b64 s[0:1], s[0:1], 14
	v_lshlrev_b32_e32 v0, 13, v0
	v_or_b32_e32 v0, s0, v0
	v_mov_b32_e32 v1, s1
	s_add_i32 s0, s4, s21
	s_lshl_b32 s1, s27, 5
	s_lshl_b32 s0, s0, 6
	s_and_b32 s1, s1, 32
	s_or_b32 s0, s0, s1
	v_lshl_add_u64 v[62:63], v[56:57], 0, v[0:1]
	v_or_b32_e32 v0, s0, v49
	v_mad_i64_i32 v[0:1], s[0:1], v0, s25, v[58:59]
	global_load_dwordx4 v[6:9], v[0:1], off
	global_load_dwordx4 v[206:209], v[0:1], off offset:32
	global_load_dwordx4 v[210:213], v[0:1], off offset:64
	global_load_dwordx4 v[214:217], v[0:1], off offset:96
	global_load_dwordx4 v[218:221], v[0:1], off offset:128
	global_load_dwordx4 v[222:225], v[0:1], off offset:160
	global_load_dwordx4 v[226:229], v[0:1], off offset:192
	global_load_dwordx4 v[230:233], v[0:1], off offset:224
	s_add_i32 s4, s4, s8
	v_lshl_add_u32 v4, s4, 9, v51
	ds_read_b128 v[10:13], v4
	ds_read_b128 v[14:17], v4 offset:16
	v_mov_b32_e32 v80, v79
	s_mov_b64 s[10:11], 0
	s_waitcnt vmcnt(7)
	v_lshlrev_b32_e32 v2, 16, v6
	v_and_b32_e32 v3, 0xffff0000, v6
	s_waitcnt lgkmcnt(1)
	v_pk_mul_f32 v[2:3], v[10:11], v[2:3]
	v_lshlrev_b32_e32 v6, 16, v7
	v_and_b32_e32 v7, 0xffff0000, v7
	v_lshlrev_b32_e32 v10, 16, v8
	v_and_b32_e32 v11, 0xffff0000, v8
	v_lshlrev_b32_e32 v8, 16, v9
	v_and_b32_e32 v9, 0xffff0000, v9
	v_pk_mul_f32 v[6:7], v[12:13], v[6:7]
	s_waitcnt lgkmcnt(0)
	v_pk_mul_f32 v[8:9], v[16:17], v[8:9]
	v_cvt_pk_bf16_f32 v17, v6, v7
	v_cvt_pk_bf16_f32 v19, v8, v9
	s_waitcnt vmcnt(6)
	v_mov_b32_e32 v6, v206
	v_mov_b32_e32 v7, v207
	v_mov_b32_e32 v8, v208
	v_mov_b32_e32 v9, v209
	v_pk_mul_f32 v[10:11], v[14:15], v[10:11]
	v_cvt_pk_bf16_f32 v16, v2, v3
	v_cvt_pk_bf16_f32 v18, v10, v11
	ds_read_b128 v[10:13], v4 offset:64
	ds_read_b128 v[20:23], v4 offset:80
	v_lshlrev_b32_e32 v2, 16, v6
	v_and_b32_e32 v3, 0xffff0000, v6
	s_waitcnt lgkmcnt(1)
	v_pk_mul_f32 v[2:3], v[10:11], v[2:3]
	v_lshlrev_b32_e32 v6, 16, v7
	v_and_b32_e32 v7, 0xffff0000, v7
	v_lshlrev_b32_e32 v10, 16, v8
	v_and_b32_e32 v11, 0xffff0000, v8
	v_lshlrev_b32_e32 v8, 16, v9
	v_and_b32_e32 v9, 0xffff0000, v9
	v_pk_mul_f32 v[6:7], v[12:13], v[6:7]
	s_waitcnt lgkmcnt(0)
	v_pk_mul_f32 v[8:9], v[22:23], v[8:9]
	v_pk_mul_f32 v[10:11], v[20:21], v[10:11]
	v_cvt_pk_bf16_f32 v21, v6, v7
	v_cvt_pk_bf16_f32 v23, v8, v9
	s_waitcnt vmcnt(5)
	v_mov_b32_e32 v6, v210
	v_mov_b32_e32 v7, v211
	v_mov_b32_e32 v8, v212
	v_mov_b32_e32 v9, v213
	v_cvt_pk_bf16_f32 v22, v10, v11
	ds_read_b128 v[10:13], v4 offset:128
	ds_read_b128 v[24:27], v4 offset:144
	v_cvt_pk_bf16_f32 v20, v2, v3
	v_lshlrev_b32_e32 v2, 16, v6
	v_and_b32_e32 v3, 0xffff0000, v6
	s_waitcnt lgkmcnt(1)
	v_pk_mul_f32 v[2:3], v[10:11], v[2:3]
	v_lshlrev_b32_e32 v6, 16, v7
	v_and_b32_e32 v7, 0xffff0000, v7
	v_lshlrev_b32_e32 v10, 16, v8
	v_and_b32_e32 v11, 0xffff0000, v8
	v_lshlrev_b32_e32 v8, 16, v9
	v_and_b32_e32 v9, 0xffff0000, v9
	v_pk_mul_f32 v[6:7], v[12:13], v[6:7]
	s_waitcnt lgkmcnt(0)
	v_pk_mul_f32 v[8:9], v[26:27], v[8:9]
	v_pk_mul_f32 v[10:11], v[24:25], v[10:11]
	v_cvt_pk_bf16_f32 v25, v6, v7
	v_cvt_pk_bf16_f32 v27, v8, v9
	s_waitcnt vmcnt(4)
	v_mov_b32_e32 v6, v214
	v_mov_b32_e32 v7, v215
	v_mov_b32_e32 v8, v216
	v_mov_b32_e32 v9, v217
	v_cvt_pk_bf16_f32 v26, v10, v11
	ds_read_b128 v[10:13], v4 offset:192
	ds_read_b128 v[28:31], v4 offset:208
	v_cvt_pk_bf16_f32 v24, v2, v3
	v_lshlrev_b32_e32 v2, 16, v6
	v_and_b32_e32 v3, 0xffff0000, v6
	s_waitcnt lgkmcnt(1)
	v_pk_mul_f32 v[2:3], v[10:11], v[2:3]
	v_lshlrev_b32_e32 v6, 16, v7
	v_and_b32_e32 v7, 0xffff0000, v7
	v_lshlrev_b32_e32 v10, 16, v8
	v_and_b32_e32 v11, 0xffff0000, v8
	v_lshlrev_b32_e32 v8, 16, v9
	v_and_b32_e32 v9, 0xffff0000, v9
	v_pk_mul_f32 v[6:7], v[12:13], v[6:7]
	s_waitcnt lgkmcnt(0)
	v_pk_mul_f32 v[8:9], v[30:31], v[8:9]
	v_pk_mul_f32 v[10:11], v[28:29], v[10:11]
	v_cvt_pk_bf16_f32 v29, v6, v7
	v_cvt_pk_bf16_f32 v31, v8, v9
	s_waitcnt vmcnt(3)
	v_mov_b32_e32 v6, v218
	v_mov_b32_e32 v7, v219
	v_mov_b32_e32 v8, v220
	v_mov_b32_e32 v9, v221
	v_cvt_pk_bf16_f32 v30, v10, v11
	ds_read_b128 v[10:13], v4 offset:256
	ds_read_b128 v[32:35], v4 offset:272
	v_cvt_pk_bf16_f32 v28, v2, v3
	v_lshlrev_b32_e32 v2, 16, v6
	v_and_b32_e32 v3, 0xffff0000, v6
	s_waitcnt lgkmcnt(1)
	v_pk_mul_f32 v[2:3], v[10:11], v[2:3]
	v_lshlrev_b32_e32 v6, 16, v7
	v_and_b32_e32 v7, 0xffff0000, v7
	v_lshlrev_b32_e32 v10, 16, v8
	v_and_b32_e32 v11, 0xffff0000, v8
	v_lshlrev_b32_e32 v8, 16, v9
	v_and_b32_e32 v9, 0xffff0000, v9
	v_pk_mul_f32 v[6:7], v[12:13], v[6:7]
	s_waitcnt lgkmcnt(0)
	v_pk_mul_f32 v[8:9], v[34:35], v[8:9]
	v_pk_mul_f32 v[10:11], v[32:33], v[10:11]
	v_cvt_pk_bf16_f32 v33, v6, v7
	v_cvt_pk_bf16_f32 v35, v8, v9
	s_waitcnt vmcnt(2)
	v_mov_b32_e32 v6, v222
	v_mov_b32_e32 v7, v223
	v_mov_b32_e32 v8, v224
	v_mov_b32_e32 v9, v225
	v_cvt_pk_bf16_f32 v34, v10, v11
	ds_read_b128 v[10:13], v4 offset:320
	ds_read_b128 v[36:39], v4 offset:336
	v_cvt_pk_bf16_f32 v32, v2, v3
	v_lshlrev_b32_e32 v2, 16, v6
	v_and_b32_e32 v3, 0xffff0000, v6
	s_waitcnt lgkmcnt(1)
	v_pk_mul_f32 v[2:3], v[10:11], v[2:3]
	v_lshlrev_b32_e32 v6, 16, v7
	v_and_b32_e32 v7, 0xffff0000, v7
	v_lshlrev_b32_e32 v10, 16, v8
	v_and_b32_e32 v11, 0xffff0000, v8
	v_lshlrev_b32_e32 v8, 16, v9
	v_and_b32_e32 v9, 0xffff0000, v9
	v_pk_mul_f32 v[6:7], v[12:13], v[6:7]
	s_waitcnt lgkmcnt(0)
	v_pk_mul_f32 v[8:9], v[38:39], v[8:9]
	v_pk_mul_f32 v[10:11], v[36:37], v[10:11]
	v_cvt_pk_bf16_f32 v37, v6, v7
	v_cvt_pk_bf16_f32 v39, v8, v9
	s_waitcnt vmcnt(1)
; #define MFMA32(a, b, c) __builtin_amdgcn_mfma_f32_32x32x16_bf16((a), (b), (c), 0, 0, 0)
; DI_ void ssd_passA(const bf16_t* xsT, const bf16_t* BT, const float* dt, const float* acum, bf16_t* Sc, unsigned char* lds, int tid, int lane, int wid) {
;     ...
; #pragma unroll 2
;             for (int nblk = 0; nblk < 4; ++nblk) {
;                 const bf16_t* bp = BT + (size_t)(g * 128 + 32 * nblk + r32) * XP + t0 + 8 * hi;
;                 f32x16 acc0;
; #pragma unroll
;                 for (int i = 0; i < 16; ++i) acc0[i] = 0.f;
; #pragma unroll
;                 for (int ks = 0; ks < 8; ++ks) acc0 = MFMA32(xa[ks], *(const bf16x8*)(bp + 16 * ks), acc0);
	v_mov_b32_e32 v6, v226
	v_mov_b32_e32 v7, v227
	v_mov_b32_e32 v8, v228
	v_mov_b32_e32 v9, v229
	v_cvt_pk_bf16_f32 v38, v10, v11
	ds_read_b128 v[10:13], v4 offset:384
	ds_read_b128 v[40:43], v4 offset:400
	v_cvt_pk_bf16_f32 v36, v2, v3
	v_lshlrev_b32_e32 v2, 16, v6
	v_and_b32_e32 v3, 0xffff0000, v6
	s_waitcnt lgkmcnt(1)
	v_pk_mul_f32 v[2:3], v[10:11], v[2:3]
	v_lshlrev_b32_e32 v10, 16, v8
	v_and_b32_e32 v11, 0xffff0000, v8
	s_waitcnt lgkmcnt(0)
	v_pk_mul_f32 v[10:11], v[40:41], v[10:11]
	v_cvt_pk_bf16_f32 v40, v2, v3
	s_waitcnt vmcnt(0)
	v_mov_b32_e32 v0, v230
	v_mov_b32_e32 v1, v231
	v_mov_b32_e32 v2, v232
	v_mov_b32_e32 v3, v233
	v_lshlrev_b32_e32 v6, 16, v7
	v_and_b32_e32 v7, 0xffff0000, v7
	v_lshlrev_b32_e32 v8, 16, v9
	v_and_b32_e32 v9, 0xffff0000, v9
	v_pk_mul_f32 v[6:7], v[12:13], v[6:7]
	v_pk_mul_f32 v[8:9], v[42:43], v[8:9]
	v_cvt_pk_bf16_f32 v41, v6, v7
	v_cvt_pk_bf16_f32 v42, v10, v11
	v_cvt_pk_bf16_f32 v43, v8, v9
	ds_read_b128 v[6:9], v4 offset:448
	ds_read_b128 v[10:13], v4 offset:464
	v_lshlrev_b32_e32 v4, 16, v0
	v_and_b32_e32 v5, 0xffff0000, v0
	s_waitcnt lgkmcnt(1)
	v_pk_mul_f32 v[4:5], v[6:7], v[4:5]
	v_lshlrev_b32_e32 v0, 16, v1
	v_and_b32_e32 v1, 0xffff0000, v1
	v_lshlrev_b32_e32 v6, 16, v2
	v_and_b32_e32 v7, 0xffff0000, v2
	v_lshlrev_b32_e32 v2, 16, v3
	v_and_b32_e32 v3, 0xffff0000, v3
	v_pk_mul_f32 v[0:1], v[8:9], v[0:1]
	s_waitcnt lgkmcnt(0)
	v_pk_mul_f32 v[6:7], v[10:11], v[6:7]
	v_pk_mul_f32 v[2:3], v[12:13], v[2:3]
	v_cvt_pk_bf16_f32 v44, v4, v5
	v_cvt_pk_bf16_f32 v45, v0, v1
	v_cvt_pk_bf16_f32 v46, v6, v7
	v_cvt_pk_bf16_f32 v47, v2, v3
	v_mad_i64_i32 v[244:245], s[0:1], v80, s25, v[60:61]
	global_load_dwordx4 v[206:209], v[244:245], off
	global_load_dwordx4 v[210:213], v[244:245], off offset:32
	global_load_dwordx4 v[214:217], v[244:245], off offset:64
	global_load_dwordx4 v[218:221], v[244:245], off offset:96
	global_load_dwordx4 v[222:225], v[244:245], off offset:128
	global_load_dwordx4 v[226:229], v[244:245], off offset:160
	global_load_dwordx4 v[236:239], v[244:245], off offset:192
	global_load_dwordx4 v[240:243], v[244:245], off offset:224
.LBB0_656:
	v_add_u32_e32 v246, 32, v80
	v_mad_i64_i32 v[234:235], s[0:1], v246, s25, v[60:61]
	v_add_u32_e32 v246, 64, v80
	v_mad_i64_i32 v[244:245], s[0:1], v246, s25, v[60:61]
	s_mov_b32 s0, 0x1a200000
	s_cmp_lg_u32 s10, 0
	s_cbranch_scc1 .Lmy_pa_second
	s_waitcnt vmcnt(7)
	v_mfma_f32_32x32x16_bf16 v[0:15], v[16:19], v[206:209], 0
	s_waitcnt vmcnt(6)
	v_mfma_f32_32x32x16_bf16 v[0:15], v[20:23], v[210:213], v[0:15]
	s_waitcnt vmcnt(5)
	v_mfma_f32_32x32x16_bf16 v[0:15], v[24:27], v[214:217], v[0:15]
	s_waitcnt vmcnt(4)
	v_mfma_f32_32x32x16_bf16 v[0:15], v[28:31], v[218:221], v[0:15]
	s_waitcnt vmcnt(3)
	v_mfma_f32_32x32x16_bf16 v[0:15], v[32:35], v[222:225], v[0:15]
	s_waitcnt vmcnt(2)
	v_mfma_f32_32x32x16_bf16 v[0:15], v[36:39], v[226:229], v[0:15]
	s_waitcnt vmcnt(1)
	v_mfma_f32_32x32x16_bf16 v[0:15], v[40:43], v[236:239], v[0:15]
	s_waitcnt vmcnt(0)
	v_mfma_f32_32x32x16_bf16 v[0:15], v[44:47], v[240:243], v[0:15]
	s_branch .Lmy_pa_join
.Lmy_pa_second:
	s_waitcnt vmcnt(15)
	v_mfma_f32_32x32x16_bf16 v[0:15], v[16:19], v[206:209], 0
	s_waitcnt vmcnt(14)
	v_mfma_f32_32x32x16_bf16 v[0:15], v[20:23], v[210:213], v[0:15]
	s_waitcnt vmcnt(13)
	v_mfma_f32_32x32x16_bf16 v[0:15], v[24:27], v[214:217], v[0:15]
	s_waitcnt vmcnt(12)
	v_mfma_f32_32x32x16_bf16 v[0:15], v[28:31], v[218:221], v[0:15]
	s_waitcnt vmcnt(11)
	v_mfma_f32_32x32x16_bf16 v[0:15], v[32:35], v[222:225], v[0:15]
	s_waitcnt vmcnt(10)
	v_mfma_f32_32x32x16_bf16 v[0:15], v[36:39], v[226:229], v[0:15]
	s_waitcnt vmcnt(9)
	v_mfma_f32_32x32x16_bf16 v[0:15], v[40:43], v[236:239], v[0:15]
	s_waitcnt vmcnt(8)
	v_mfma_f32_32x32x16_bf16 v[0:15], v[44:47], v[240:243], v[0:15]
; DI_ unsigned pk2(float lo, float hi) { typedef float f2 __attribute__((ext_vector_type(2))); typedef __bf16 b2 __attribute__((ext_vector_type(2))); f2 v = {lo, hi}; b2 b = __builtin_convertvector(v, b2); return __builtin_bit_cast(unsigned, b); }
; #define MFMA32(a, b, c) __builtin_amdgcn_mfma_f32_32x32x16_bf16((a), (b), (c), 0, 0, 0)
; DI_ int crow(int r, int hi) { return (r & 3) + 8 * (r >> 2) + 4 * hi; }
; DI_ void ssd_passA(const bf16_t* xsT, const bf16_t* BT, const float* dt, const float* acum, bf16_t* Sc, unsigned char* lds, int tid, int lane, int wid) {
;     ...
;             for (int nblk = 0; nblk < 4; ++nblk) {
;                 const bf16_t* bp = BT + (size_t)(g * 128 + 32 * nblk + r32) * XP + t0 + 8 * hi;
;                 f32x16 acc0;
; #pragma unroll
;                 for (int i = 0; i < 16; ++i) acc0[i] = 0.f;
; #pragma unroll
;                 for (int ks = 0; ks < 8; ++ks) acc0 = MFMA32(xa[ks], *(const bf16x8*)(bp + 16 * ks), acc0);
;                 bf16_t* so = Sc + ((size_t)(c * SHEADS + hA + h2) * 64 + 32 * pblk) * 128 + 32 * nblk + (r32 & ~1);
; #pragma unroll
;                 for (int k = 0; k < 8; ++k) {
;                     const float ve = acc0[2 * k], vo = acc0[2 * k + 1];
;                     const float send = (lane & 1) ? ve : vo, recv = __shfl_xor(send, 1);
;                     const unsigned w = (lane & 1) ? pk2(recv, vo) : pk2(ve, recv);
;                     *(unsigned*)(so + (size_t)crow(2 * k + (lane & 1), hi) * 128) = w;
;                 }
.Lmy_pa_join:
	global_load_dwordx4 v[206:209], v[234:235], off
	global_load_dwordx4 v[210:213], v[234:235], off offset:32
	global_load_dwordx4 v[214:217], v[234:235], off offset:64
	global_load_dwordx4 v[218:221], v[234:235], off offset:96
	global_load_dwordx4 v[222:225], v[234:235], off offset:128
	global_load_dwordx4 v[226:229], v[234:235], off offset:160
	global_load_dwordx4 v[236:239], v[234:235], off offset:192
	global_load_dwordx4 v[240:243], v[234:235], off offset:224
	s_nop 11
	v_cndmask_b32_e32 v64, v0, v1, vcc
	ds_bpermute_b32 v64, v70, v64
	s_waitcnt lgkmcnt(0)
	v_cndmask_b32_e32 v1, v1, v64, vcc
	v_cndmask_b32_e32 v0, v64, v0, vcc
	v_cvt_pk_bf16_f32 v68, v0, v1
	v_lshl_add_u64 v[0:1], v[62:63], 0, s[10:11]
	v_add_co_u32_e64 v66, s[0:1], s0, v0
	s_add_u32 s10, s10, 0x80
	s_nop 0
	v_addc_co_u32_e64 v67, s[0:1], 0, v1, s[0:1]
	s_mov_b32 s0, 0x1a201000
	s_nop 0
	v_add_co_u32_e64 v64, s[0:1], s0, v0
	v_cndmask_b32_e32 v0, v2, v3, vcc
	ds_bpermute_b32 v0, v70, v0
	v_addc_co_u32_e64 v65, s[0:1], 0, v1, s[0:1]
	global_store_dword v[64:65], v68, off offset:-4096
	s_addc_u32 s11, s11, 0
	s_waitcnt lgkmcnt(0)
	v_cndmask_b32_e32 v1, v3, v0, vcc
	v_cndmask_b32_e32 v0, v0, v2, vcc
	v_cvt_pk_bf16_f32 v0, v0, v1
	global_store_dword v[66:67], v0, off offset:512
	v_cndmask_b32_e32 v0, v4, v5, vcc
	ds_bpermute_b32 v0, v70, v0
	s_cmpk_eq_i32 s10, 0x100
	s_waitcnt lgkmcnt(0)
	v_cndmask_b32_e32 v1, v5, v0, vcc
	v_cndmask_b32_e32 v0, v0, v4, vcc
	v_cvt_pk_bf16_f32 v0, v0, v1
	global_store_dword v[66:67], v0, off offset:2048
	v_cndmask_b32_e32 v0, v6, v7, vcc
	ds_bpermute_b32 v0, v70, v0
	s_waitcnt lgkmcnt(0)
	v_cndmask_b32_e32 v1, v7, v0, vcc
	v_cndmask_b32_e32 v0, v0, v6, vcc
	v_cvt_pk_bf16_f32 v0, v0, v1
	global_store_dword v[66:67], v0, off offset:2560
	v_cndmask_b32_e32 v0, v8, v9, vcc
	ds_bpermute_b32 v0, v70, v0
	s_waitcnt lgkmcnt(0)
	v_cndmask_b32_e32 v1, v9, v0, vcc
	v_cndmask_b32_e32 v0, v0, v8, vcc
	v_cvt_pk_bf16_f32 v0, v0, v1
	global_store_dword v[64:65], v0, off
	v_cndmask_b32_e32 v0, v10, v11, vcc
	ds_bpermute_b32 v0, v70, v0
	s_waitcnt lgkmcnt(0)
	v_cndmask_b32_e32 v1, v11, v0, vcc
	v_cndmask_b32_e32 v0, v0, v10, vcc
	v_cvt_pk_bf16_f32 v0, v0, v1
	global_store_dword v[64:65], v0, off offset:512
	v_cndmask_b32_e32 v0, v12, v13, vcc
	ds_bpermute_b32 v0, v70, v0
	s_waitcnt lgkmcnt(0)
	v_cndmask_b32_e32 v1, v13, v0, vcc
	v_cndmask_b32_e32 v0, v0, v12, vcc
	v_cvt_pk_bf16_f32 v0, v0, v1
	global_store_dword v[64:65], v0, off offset:2048
	v_cndmask_b32_e32 v0, v14, v15, vcc
	ds_bpermute_b32 v0, v70, v0
	s_waitcnt lgkmcnt(0)
	v_cndmask_b32_e32 v1, v15, v0, vcc
	v_cndmask_b32_e32 v0, v0, v14, vcc
	v_cvt_pk_bf16_f32 v0, v0, v1
	global_store_dword v[64:65], v0, off offset:2560
	v_add_u32_e32 v80, 64, v80
	s_waitcnt vmcnt(15)
	v_mfma_f32_32x32x16_bf16 v[0:15], v[16:19], v[206:209], 0
	s_waitcnt vmcnt(14)
	v_mfma_f32_32x32x16_bf16 v[0:15], v[20:23], v[210:213], v[0:15]
	s_waitcnt vmcnt(13)
	v_mfma_f32_32x32x16_bf16 v[0:15], v[24:27], v[214:217], v[0:15]
	s_waitcnt vmcnt(12)
	v_mfma_f32_32x32x16_bf16 v[0:15], v[28:31], v[218:221], v[0:15]
	s_waitcnt vmcnt(11)
	v_mfma_f32_32x32x16_bf16 v[0:15], v[32:35], v[222:225], v[0:15]
	s_waitcnt vmcnt(10)
	v_mfma_f32_32x32x16_bf16 v[0:15], v[36:39], v[226:229], v[0:15]
	s_waitcnt vmcnt(9)
	v_mfma_f32_32x32x16_bf16 v[0:15], v[40:43], v[236:239], v[0:15]
	s_waitcnt vmcnt(8)
	v_mfma_f32_32x32x16_bf16 v[0:15], v[44:47], v[240:243], v[0:15]
	s_cbranch_scc1 .Lmy_pa_nopf
	global_load_dwordx4 v[206:209], v[244:245], off
	global_load_dwordx4 v[210:213], v[244:245], off offset:32
	global_load_dwordx4 v[214:217], v[244:245], off offset:64
	global_load_dwordx4 v[218:221], v[244:245], off offset:96
	global_load_dwordx4 v[222:225], v[244:245], off offset:128
	global_load_dwordx4 v[226:229], v[244:245], off offset:160
	global_load_dwordx4 v[236:239], v[244:245], off offset:192
	global_load_dwordx4 v[240:243], v[244:245], off offset:224
.Lmy_pa_nopf:
	s_nop 11
	v_cndmask_b32_e32 v68, v0, v1, vcc
	ds_bpermute_b32 v68, v70, v68
	s_waitcnt lgkmcnt(0)
	v_cndmask_b32_e32 v1, v1, v68, vcc
	v_cndmask_b32_e32 v0, v68, v0, vcc
	v_cvt_pk_bf16_f32 v0, v0, v1
	global_store_dword v[66:67], v0, off offset:64
	v_cndmask_b32_e32 v0, v2, v3, vcc
	ds_bpermute_b32 v0, v70, v0
	s_waitcnt lgkmcnt(0)
	v_cndmask_b32_e32 v1, v3, v0, vcc
	v_cndmask_b32_e32 v0, v0, v2, vcc
	v_cvt_pk_bf16_f32 v0, v0, v1
	global_store_dword v[66:67], v0, off offset:576
	v_cndmask_b32_e32 v0, v4, v5, vcc
	ds_bpermute_b32 v0, v70, v0
	s_waitcnt lgkmcnt(0)
	v_cndmask_b32_e32 v1, v5, v0, vcc
	v_cndmask_b32_e32 v0, v0, v4, vcc
	v_cvt_pk_bf16_f32 v0, v0, v1
	global_store_dword v[66:67], v0, off offset:2112
	v_cndmask_b32_e32 v0, v6, v7, vcc
	ds_bpermute_b32 v0, v70, v0
	s_waitcnt lgkmcnt(0)
	v_cndmask_b32_e32 v1, v7, v0, vcc
	v_cndmask_b32_e32 v0, v0, v6, vcc
	v_cvt_pk_bf16_f32 v0, v0, v1
	global_store_dword v[66:67], v0, off offset:2624
	v_cndmask_b32_e32 v0, v8, v9, vcc
	ds_bpermute_b32 v0, v70, v0
	s_waitcnt lgkmcnt(0)
	v_cndmask_b32_e32 v1, v9, v0, vcc
	v_cndmask_b32_e32 v0, v0, v8, vcc
	v_cvt_pk_bf16_f32 v0, v0, v1
	global_store_dword v[64:65], v0, off offset:64
	v_cndmask_b32_e32 v0, v10, v11, vcc
	ds_bpermute_b32 v0, v70, v0
	s_waitcnt lgkmcnt(0)
	v_cndmask_b32_e32 v1, v11, v0, vcc
	v_cndmask_b32_e32 v0, v0, v10, vcc
	v_cvt_pk_bf16_f32 v0, v0, v1
	global_store_dword v[64:65], v0, off offset:576
	v_cndmask_b32_e32 v0, v12, v13, vcc
	ds_bpermute_b32 v0, v70, v0
	s_waitcnt lgkmcnt(0)
	v_cndmask_b32_e32 v1, v13, v0, vcc
	v_cndmask_b32_e32 v0, v0, v12, vcc
	v_cvt_pk_bf16_f32 v0, v0, v1
	global_store_dword v[64:65], v0, off offset:2112
	v_cndmask_b32_e32 v0, v14, v15, vcc
	ds_bpermute_b32 v0, v70, v0
	s_waitcnt lgkmcnt(0)
	v_cndmask_b32_e32 v1, v15, v0, vcc
	v_cndmask_b32_e32 v0, v0, v14, vcc
	v_cvt_pk_bf16_f32 v0, v0, v1
	global_store_dword v[64:65], v0, off offset:2624
	s_cbranch_scc0 .LBB0_656
	s_add_i32 s27, s27, 1
	s_xor_b64 s[6:7], s[6:7], -1
	s_cmp_eq_u32 s27, 4
	s_cbranch_scc0 .LBB0_655
	v_readlane_b32 s0, v254, 6
	s_add_i32 s20, s20, s92
	s_add_i32 s19, s19, s0
	s_cmpk_gt_i32 s20, 0xff
	s_barrier
	s_cbranch_scc0 .LBB0_654
	v_readlane_b32 s26, v254, 36
	v_readlane_b32 s27, v254, 37
